# small_gemm (sample rows) in all 10 GEMM phases: all operand loads hoisted ahead of MFMAs (1 round trip instead of per-kstep)
# baseline (speedup 1.0000x reference)
;     __device__ __forceinline__ float apply8(int r, int c, const f32x4 a0, const f32x4 a1) const {
;         const float* xrow = r < MP_ROWS ? xp + (size_t)r * D : xs + (size_t)(r - MP_ROWS) * D;
;     ...
;     for (int tile = first; tile < 8 * ncol_tiles; tile += stride) {
;         const int rt = tile & 7, ct = tile >> 3, r0 = MP_ROWS + 32 * rt, c0 = 32 * ct;
;         const bf16_t* ap = A + (size_t)(r0 + fr) * lda + (c0 >> 8) * a_grp_off + wid * kw + 8 * fq;
;         const bf16_t* bp = Bt + (size_t)(c0 + fr) * ldb + wid * kw + 8 * fq;
;         f32x4 acc[2][2];
; #pragma unroll
;         for (int i = 0; i < 2; ++i)
; #pragma unroll
;             for (int j = 0; j < 2; ++j) acc[i][j] = (f32x4){0.f, 0.f, 0.f, 0.f};
;         for (int s0 = 0; s0 < ksteps; s0 += 4) {
;             bf16x8 a0[4], a1[4], b0[4], b1[4];
; #pragma unroll
;             for (int j = 0; j < 4; ++j) if (s0 + j < ksteps) { const int s = s0 + j;
;                 a0[j] = *(const bf16x8*)(ap + 32 * s); a1[j] = *(const bf16x8*)(ap + (size_t)16 * lda + 32 * s);
;                 b0[j] = *(const bf16x8*)(bp + 32 * s); b1[j] = *(const bf16x8*)(bp + (size_t)16 * ldb + 32 * s); }
; #pragma unroll
;             for (int j = 0; j < 4; ++j) if (s0 + j < ksteps) {
;                 acc[0][0] = __builtin_amdgcn_mfma_f32_16x16x32_bf16(b0[j], a0[j], acc[0][0], 0, 0, 0); acc[0][1] = __builtin_amdgcn_mfma_f32_16x16x32_bf16(b1[j], a0[j], acc[0][1], 0, 0, 0);
;                 acc[1][0] = __builtin_amdgcn_mfma_f32_16x16x32_bf16(b0[j], a1[j], acc[1][0], 0, 0, 0); acc[1][1] = __builtin_amdgcn_mfma_f32_16x16x32_bf16(b1[j], a1[j], acc[1][1], 0, 0, 0); } }
; #pragma unroll
;         for (int i = 0; i < 2; ++i)
; #pragma unroll
;             for (int j = 0; j < 2; ++j) *(f32x4*)(part + (wid * 32 + 16 * i + fr) * 36 + 16 * j + 4 * fq) = acc[i][j];
;         __syncthreads();
;         if (tid < 128) { const int row = tid >> 2, oct = tid & 3; f32x4 v0 = (f32x4){0.f, 0.f, 0.f, 0.f}, v1 = v0;
; #pragma unroll
;             for (int w = 0; w < 8; ++w) { v0 += *(const f32x4*)(part + (w * 32 + row) * 36 + 8 * oct); v1 += *(const f32x4*)(part + (w * 32 + row) * 36 + 8 * oct + 4); }
;             float sq = E.apply8(r0 + row, c0 + 8 * oct, v0, v1);
;             if (Epi::HAS_SSQ) { sq += __shfl_xor(sq, 1); sq += __shfl_xor(sq, 2); if (oct == 0) atomicAdd(E.ssq + r0 + row, sq); } }
.LBB0_1465:
	s_and_b32 s31, s3, 0xffffffe0
	v_or_b32_e32 v0, s31, v80
	s_and_b32 s10, s25, 0xe0
	v_ashrrev_i32_e32 v1, 31, v0
	s_bitset1_b32 s10, 14
	v_lshlrev_b64 v[0:1], 9, v[0:1]
	v_lshl_add_u64 v[8:9], v[68:69], 0, v[0:1]
	v_or_b32_e32 v0, s10, v80
	v_lshlrev_b32_e32 v66, 11, v0
	s_and_b32 s8, s3, 0xffffff00
	v_lshl_add_u64 v[4:5], s[74:75], 0, v[66:67]
	s_ashr_i32 s9, s8, 31
	v_lshl_add_u64 v[4:5], s[8:9], 1, v[4:5]
	v_lshl_add_u64 v[4:5], v[64:65], 1, v[4:5]
	v_add_co_u32_e64 v16, s[8:9], s28, v8
	v_lshl_add_u64 v[10:11], v[4:5], 0, v[74:75]
	v_addc_co_u32_e64 v17, s[8:9], 0, v9, s[8:9]
	v_add_co_u32_e64 v12, s[8:9], s27, v10
	v_addc_co_u32_e64 v13, s[8:9], 0, v11, s[8:9]
	global_load_dwordx4 v[18:21], v[8:9], off
	global_load_dwordx4 v[22:25], v[10:11], off
	global_load_dwordx4 v[26:29], v[12:13], off
	global_load_dwordx4 v[30:33], v[16:17], off
	s_waitcnt vmcnt(2)
	v_mfma_f32_16x16x32_bf16 v[34:37], v[18:21], v[22:25], 0
	s_waitcnt vmcnt(1)
	v_mfma_f32_16x16x32_bf16 v[38:41], v[18:21], v[26:29], 0
	s_waitcnt vmcnt(0)
	v_mfma_f32_16x16x32_bf16 v[42:45], v[30:33], v[22:25], 0
	v_mfma_f32_16x16x32_bf16 v[46:49], v[30:33], v[26:29], 0
	s_nop 9
	ds_write_b128 v71, v[34:37]
	ds_write_b128 v71, v[38:41] offset:2304
	ds_write_b128 v71, v[42:45] offset:64
	ds_write_b128 v71, v[46:49] offset:2368
	s_waitcnt lgkmcnt(0)
	s_barrier
	s_and_saveexec_b64 s[22:23], vcc
	s_cbranch_execz .LBB0_1464
	ds_read_b128 v[60:63], v82
	ds_read_b128 v[56:59], v82 offset:16
	ds_read_b128 v[52:55], v82 offset:4608
	ds_read_b128 v[48:51], v82 offset:4624
	ds_read_b128 v[44:47], v82 offset:9216
	ds_read_b128 v[40:43], v82 offset:9232
	ds_read_b128 v[36:39], v82 offset:13824
	ds_read_b128 v[32:35], v82 offset:13840
	ds_read_b128 v[28:31], v82 offset:18432
	ds_read_b128 v[24:27], v82 offset:18448
	ds_read_b128 v[20:23], v82 offset:23040
	ds_read_b128 v[16:19], v82 offset:23056
	ds_read_b128 v[12:15], v82 offset:27648
	ds_read_b128 v[8:11], v82 offset:27664
	ds_read_b128 v[4:7], v82 offset:32256
	ds_read_b128 v[0:3], v82 offset:32272
	v_add_u32_e32 v76, s10, v70
	v_cmp_lt_i32_e64 s[8:9], s29, v76
	s_and_saveexec_b64 s[34:35], s[8:9]
	s_xor_b64 s[8:9], exec, s[34:35]
	v_add_u32_e32 v66, 0xffffc000, v76
	v_lshlrev_b64 v[78:79], 12, v[66:67]
	v_lshl_add_u64 v[78:79], s[14:15], 0, v[78:79]
	v_mov_b32_e32 v77, v67
	s_andn2_saveexec_b64 s[8:9], s[8:9]
	v_ashrrev_i32_e32 v77, 31, v76
	v_lshlrev_b64 v[78:79], 12, v[76:77]
	v_lshl_add_u64 v[78:79], s[12:13], 0, v[78:79]
	s_or_b64 exec, exec, s[8:9]
	v_or_b32_e32 v108, s31, v81
	v_ashrrev_i32_e32 v109, 31, v108
	v_lshlrev_b64 v[110:111], 2, v[108:109]
	v_lshl_add_u64 v[88:89], s[16:17], 0, v[110:111]
	global_load_dwordx4 v[84:87], v[88:89], off offset:16
	s_nop 0
	global_load_dwordx4 v[88:91], v[88:89], off
	v_lshl_add_u64 v[104:105], s[18:19], 0, v[110:111]
	v_lshl_add_u64 v[78:79], v[78:79], 0, v[110:111]
	global_load_dwordx4 v[92:95], v[104:105], off
	global_load_dwordx4 v[96:99], v[78:79], off
	global_load_dwordx4 v[100:103], v[78:79], off offset:16
	s_nop 0
	global_load_dwordx4 v[104:107], v[104:105], off offset:16
	s_waitcnt lgkmcnt(14)
	v_pk_add_f32 v[62:63], v[62:63], 0 op_sel_hi:[1,0]
	v_pk_add_f32 v[60:61], v[60:61], 0 op_sel_hi:[1,0]
	v_pk_add_f32 v[58:59], v[58:59], 0 op_sel_hi:[1,0]
	v_pk_add_f32 v[56:57], v[56:57], 0 op_sel_hi:[1,0]
	s_waitcnt lgkmcnt(13)
	v_pk_add_f32 v[54:55], v[62:63], v[54:55]
	v_pk_add_f32 v[52:53], v[60:61], v[52:53]
	s_waitcnt lgkmcnt(12)
	v_pk_add_f32 v[50:51], v[58:59], v[50:51]
	v_pk_add_f32 v[48:49], v[56:57], v[48:49]
	s_waitcnt lgkmcnt(11)
	v_pk_add_f32 v[46:47], v[54:55], v[46:47]
	v_pk_add_f32 v[44:45], v[52:53], v[44:45]
	s_waitcnt lgkmcnt(10)
	v_pk_add_f32 v[42:43], v[50:51], v[42:43]
	v_pk_add_f32 v[40:41], v[48:49], v[40:41]
	s_waitcnt lgkmcnt(9)
	v_pk_add_f32 v[38:39], v[46:47], v[38:39]
	v_pk_add_f32 v[36:37], v[44:45], v[36:37]
	s_waitcnt lgkmcnt(8)
	v_pk_add_f32 v[34:35], v[42:43], v[34:35]
	v_pk_add_f32 v[32:33], v[40:41], v[32:33]
	s_waitcnt lgkmcnt(7)
	v_pk_add_f32 v[30:31], v[38:39], v[30:31]
	v_pk_add_f32 v[28:29], v[36:37], v[28:29]
	s_waitcnt lgkmcnt(6)
	v_pk_add_f32 v[26:27], v[34:35], v[26:27]
	v_pk_add_f32 v[24:25], v[32:33], v[24:25]
	s_waitcnt lgkmcnt(5)
	v_pk_add_f32 v[22:23], v[30:31], v[22:23]
	v_pk_add_f32 v[20:21], v[28:29], v[20:21]
	s_waitcnt lgkmcnt(4)
	v_pk_add_f32 v[18:19], v[26:27], v[18:19]
	v_pk_add_f32 v[16:17], v[24:25], v[16:17]
	s_waitcnt lgkmcnt(3)
	v_pk_add_f32 v[14:15], v[22:23], v[14:15]
	v_pk_add_f32 v[12:13], v[20:21], v[12:13]
	s_waitcnt lgkmcnt(2)
	v_pk_add_f32 v[10:11], v[18:19], v[10:11]
	v_pk_add_f32 v[8:9], v[16:17], v[8:9]
	s_waitcnt lgkmcnt(1)
	v_pk_add_f32 v[6:7], v[14:15], v[6:7]
	v_pk_add_f32 v[4:5], v[12:13], v[4:5]
	s_waitcnt lgkmcnt(0)
	v_pk_add_f32 v[2:3], v[10:11], v[2:3]
	v_pk_add_f32 v[0:1], v[8:9], v[0:1]
	v_and_b32_e32 v112, 64, v83
	v_xor_b32_e32 v66, 1, v83
	v_add_u32_e32 v58, 64, v112
	v_cmp_lt_i32_e64 s[8:9], v66, v58
	v_lshlrev_b64 v[78:79], 12, v[76:77]
	v_xor_b32_e32 v113, 2, v83
	v_cndmask_b32_e64 v48, v83, v66, s[8:9]
	v_lshlrev_b32_e32 v42, 2, v48
	v_lshl_add_u64 v[56:57], s[52:53], 0, v[78:79]
	v_cmp_lt_i32_e64 s[8:9], v113, v58
	v_lshl_add_u64 v[40:41], v[56:57], 0, v[110:111]
	s_waitcnt vmcnt(5)
	v_pk_add_f32 v[8:9], v[2:3], v[86:87]
	s_waitcnt vmcnt(4)
	v_pk_add_f32 v[6:7], v[6:7], v[90:91]
	v_pk_add_f32 v[4:5], v[4:5], v[88:89]
	v_pk_add_f32 v[10:11], v[0:1], v[84:85]
	s_waitcnt vmcnt(2)
	v_pk_fma_f32 v[2:3], v[6:7], v[94:95], v[98:99]
	v_pk_fma_f32 v[0:1], v[4:5], v[92:93], v[96:97]
	s_waitcnt vmcnt(0)
	v_pk_fma_f32 v[6:7], v[8:9], v[106:107], v[102:103]
	v_pk_fma_f32 v[4:5], v[10:11], v[104:105], v[100:101]
	v_mul_f32_e32 v8, v1, v1
	v_mul_f32_e32 v9, v3, v3
	v_mul_f32_e32 v10, v5, v5
	v_fmac_f32_e32 v8, v0, v0
	v_fmac_f32_e32 v9, v2, v2
	v_mul_f32_e32 v11, v7, v7
	v_fmac_f32_e32 v10, v4, v4
	v_add_f32_e32 v8, v8, v9
	v_fmac_f32_e32 v11, v6, v6
	v_add_f32_e32 v8, v8, v10
	v_add_f32_e32 v12, v11, v8
	ds_bpermute_b32 v13, v42, v12
	v_cndmask_b32_e64 v49, v83, v113, s[8:9]
	global_store_dwordx4 v[40:41], v[0:3], off
	global_store_dwordx4 v[40:41], v[4:7], off offset:16
	v_cvt_pk_bf16_f32 v8, v0, v1
	v_cvt_pk_bf16_f32 v9, v2, v3
	v_cvt_pk_bf16_f32 v10, v4, v5
	v_cvt_pk_bf16_f32 v11, v6, v7
	s_waitcnt lgkmcnt(0)
	v_add_f32_e32 v0, v12, v13
	v_lshlrev_b32_e32 v1, 2, v49
	ds_bpermute_b32 v1, v1, v0
	v_lshlrev_b64 v[2:3], 11, v[76:77]
	v_lshl_add_u64 v[2:3], s[70:71], 0, v[2:3]
	v_lshl_add_u64 v[2:3], v[108:109], 1, v[2:3]
	global_store_dwordx4 v[2:3], v[8:11], off
	s_and_b64 exec, exec, s[6:7]
	s_cbranch_execz .LBB0_1464
	s_lshl_b32 s10, s10, 2
	v_lshl_add_u64 v[2:3], v[72:73], 0, s[10:11]
	s_waitcnt lgkmcnt(0)
	v_add_f32_e32 v0, v0, v1
	global_atomic_add_f32 v[2:3], v0, off
	s_branch .LBB0_1464

;     __device__ __forceinline__ float apply8(int r, int c, const f32x4 a0, const f32x4 a1) const { *(u32x4*)(O + (size_t)r * ldc + c) = pack8(a0, a1); return 0.f; }
;     ...
;     for (int tile = first; tile < 8 * ncol_tiles; tile += stride) {
;         const int rt = tile & 7, ct = tile >> 3, r0 = MP_ROWS + 32 * rt, c0 = 32 * ct;
;         const bf16_t* ap = A + (size_t)(r0 + fr) * lda + (c0 >> 8) * a_grp_off + wid * kw + 8 * fq;
;         const bf16_t* bp = Bt + (size_t)(c0 + fr) * ldb + wid * kw + 8 * fq;
;         f32x4 acc[2][2];
; #pragma unroll
;         for (int i = 0; i < 2; ++i)
; #pragma unroll
;             for (int j = 0; j < 2; ++j) acc[i][j] = (f32x4){0.f, 0.f, 0.f, 0.f};
;         for (int s0 = 0; s0 < ksteps; s0 += 4) {
;             bf16x8 a0[4], a1[4], b0[4], b1[4];
; #pragma unroll
;             for (int j = 0; j < 4; ++j) if (s0 + j < ksteps) { const int s = s0 + j;
;                 a0[j] = *(const bf16x8*)(ap + 32 * s); a1[j] = *(const bf16x8*)(ap + (size_t)16 * lda + 32 * s);
;                 b0[j] = *(const bf16x8*)(bp + 32 * s); b1[j] = *(const bf16x8*)(bp + (size_t)16 * ldb + 32 * s); }
; #pragma unroll
;             for (int j = 0; j < 4; ++j) if (s0 + j < ksteps) {
;                 acc[0][0] = __builtin_amdgcn_mfma_f32_16x16x32_bf16(b0[j], a0[j], acc[0][0], 0, 0, 0); acc[0][1] = __builtin_amdgcn_mfma_f32_16x16x32_bf16(b1[j], a0[j], acc[0][1], 0, 0, 0);
;                 acc[1][0] = __builtin_amdgcn_mfma_f32_16x16x32_bf16(b0[j], a1[j], acc[1][0], 0, 0, 0); acc[1][1] = __builtin_amdgcn_mfma_f32_16x16x32_bf16(b1[j], a1[j], acc[1][1], 0, 0, 0); } }
; #pragma unroll
;         for (int i = 0; i < 2; ++i)
; #pragma unroll
;             for (int j = 0; j < 2; ++j) *(f32x4*)(part + (wid * 32 + 16 * i + fr) * 36 + 16 * j + 4 * fq) = acc[i][j];
;         __syncthreads();
;         if (tid < 128) { const int row = tid >> 2, oct = tid & 3; f32x4 v0 = (f32x4){0.f, 0.f, 0.f, 0.f}, v1 = v0;
; #pragma unroll
;             for (int w = 0; w < 8; ++w) { v0 += *(const f32x4*)(part + (w * 32 + row) * 36 + 8 * oct); v1 += *(const f32x4*)(part + (w * 32 + row) * 36 + 8 * oct + 4); }
;             float sq = E.apply8(r0 + row, c0 + 8 * oct, v0, v1);
;             if (Epi::HAS_SSQ) { sq += __shfl_xor(sq, 1); sq += __shfl_xor(sq, 2); if (oct == 0) atomicAdd(E.ssq + r0 + row, sq); } }
;         __syncthreads();
.LBB0_1573:
	s_and_b32 s17, s11, 0xffffffe0
	v_or_b32_e32 v12, s17, v6
	v_ashrrev_i32_e32 v13, 31, v12
	s_and_b32 s16, s13, 0xe0
	v_lshlrev_b64 v[12:13], 9, v[12:13]
	s_bitset1_b32 s16, 14
	v_lshl_add_u64 v[20:21], v[4:5], 0, v[12:13]
	v_or_b32_e32 v0, s16, v6
	v_lshlrev_b32_e32 v0, 9, v0
	v_lshl_add_u64 v[22:23], v[2:3], 0, v[0:1]
	v_add_co_u32_e32 v32, vcc, s15, v22
	v_addc_co_u32_e32 v33, vcc, 0, v23, vcc
	v_add_co_u32_e32 v34, vcc, s15, v20
	v_addc_co_u32_e32 v35, vcc, 0, v21, vcc
	global_load_dwordx4 v[14:17], v[20:21], off
	global_load_dwordx4 v[24:27], v[22:23], off
	global_load_dwordx4 v[28:31], v[32:33], off
	global_load_dwordx4 v[36:39], v[34:35], off
	s_waitcnt vmcnt(2)
	v_mfma_f32_16x16x32_bf16 v[40:43], v[14:17], v[24:27], 0
	s_waitcnt vmcnt(1)
	v_mfma_f32_16x16x32_bf16 v[44:47], v[14:17], v[28:31], 0
	s_waitcnt vmcnt(0)
	v_mfma_f32_16x16x32_bf16 v[48:51], v[36:39], v[24:27], 0
	v_mfma_f32_16x16x32_bf16 v[52:55], v[36:39], v[28:31], 0
	s_nop 9
	ds_write_b128 v9, v[40:43]
	ds_write_b128 v9, v[44:47] offset:2304
	ds_write_b128 v9, v[48:51] offset:64
	ds_write_b128 v9, v[52:55] offset:2368
	s_waitcnt lgkmcnt(0)
	s_barrier
	s_and_saveexec_b64 s[8:9], s[6:7]
	s_cbranch_execz .LBB0_1572
	ds_read_b128 v[12:15], v10
	ds_read_b128 v[16:19], v10 offset:16
	ds_read_b128 v[20:23], v10 offset:4608
	s_waitcnt lgkmcnt(2)
	v_pk_add_f32 v[24:25], v[14:15], 0 op_sel_hi:[1,0]
	v_pk_add_f32 v[26:27], v[12:13], 0 op_sel_hi:[1,0]
	ds_read_b128 v[12:15], v10 offset:4624
	s_waitcnt lgkmcnt(2)
	v_pk_add_f32 v[28:29], v[18:19], 0 op_sel_hi:[1,0]
	v_pk_add_f32 v[30:31], v[16:17], 0 op_sel_hi:[1,0]
	ds_read_b128 v[16:19], v10 offset:9216
	s_waitcnt lgkmcnt(2)
	v_pk_add_f32 v[24:25], v[24:25], v[22:23]
	v_pk_add_f32 v[26:27], v[26:27], v[20:21]
	s_waitcnt lgkmcnt(1)
	v_pk_add_f32 v[28:29], v[28:29], v[14:15]
	ds_read_b128 v[20:23], v10 offset:9232
	v_pk_add_f32 v[30:31], v[30:31], v[12:13]
	ds_read_b128 v[12:15], v10 offset:13824
	s_waitcnt lgkmcnt(2)
	v_pk_add_f32 v[24:25], v[24:25], v[18:19]
	v_pk_add_f32 v[26:27], v[26:27], v[16:17]
	ds_read_b128 v[16:19], v10 offset:13840
	s_waitcnt lgkmcnt(2)
	v_pk_add_f32 v[28:29], v[28:29], v[22:23]
	v_pk_add_f32 v[30:31], v[30:31], v[20:21]
	s_waitcnt lgkmcnt(1)
	v_pk_add_f32 v[24:25], v[24:25], v[14:15]
	ds_read_b128 v[20:23], v10 offset:18432
	v_pk_add_f32 v[26:27], v[26:27], v[12:13]
	ds_read_b128 v[12:15], v10 offset:18448
	s_waitcnt lgkmcnt(2)
	v_pk_add_f32 v[28:29], v[28:29], v[18:19]
	v_pk_add_f32 v[30:31], v[30:31], v[16:17]
	ds_read_b128 v[16:19], v10 offset:23040
	s_waitcnt lgkmcnt(2)
	v_pk_add_f32 v[24:25], v[24:25], v[22:23]
	v_pk_add_f32 v[26:27], v[26:27], v[20:21]
	s_waitcnt lgkmcnt(1)
	v_pk_add_f32 v[28:29], v[28:29], v[14:15]
	ds_read_b128 v[20:23], v10 offset:23056
	v_pk_add_f32 v[30:31], v[30:31], v[12:13]
	ds_read_b128 v[12:15], v10 offset:27648
	s_waitcnt lgkmcnt(2)
	v_pk_add_f32 v[24:25], v[24:25], v[18:19]
	v_pk_add_f32 v[26:27], v[26:27], v[16:17]
	ds_read_b128 v[16:19], v10 offset:27664
	s_waitcnt lgkmcnt(2)
	v_pk_add_f32 v[28:29], v[28:29], v[22:23]
	s_waitcnt lgkmcnt(1)
	v_pk_add_f32 v[24:25], v[24:25], v[14:15]
	v_pk_add_f32 v[26:27], v[26:27], v[12:13]
	ds_read_b128 v[12:15], v10 offset:32272
	v_pk_add_f32 v[30:31], v[30:31], v[20:21]
	ds_read_b128 v[20:23], v10 offset:32256
	s_waitcnt lgkmcnt(2)
	v_pk_add_f32 v[18:19], v[28:29], v[18:19]
	v_pk_add_f32 v[16:17], v[30:31], v[16:17]
	s_waitcnt lgkmcnt(1)
	v_pk_add_f32 v[18:19], v[18:19], v[14:15]
	v_pk_add_f32 v[14:15], v[16:17], v[12:13]
	v_add_u32_e32 v16, s16, v7
	v_ashrrev_i32_e32 v17, 31, v16
	s_waitcnt lgkmcnt(0)
	v_pk_add_f32 v[22:23], v[24:25], v[22:23]
	v_or_b32_e32 v24, s17, v8
	v_lshlrev_b64 v[16:17], 11, v[16:17]
	v_lshl_add_u64 v[16:17], s[72:73], 0, v[16:17]
	v_ashrrev_i32_e32 v25, 31, v24
	v_lshl_add_u64 v[16:17], v[24:25], 1, v[16:17]
	v_pk_add_f32 v[20:21], v[26:27], v[20:21]
	s_nop 0
	v_cvt_pk_bf16_f32 v12, v20, v21
	v_cvt_pk_bf16_f32 v13, v22, v23
	v_cvt_pk_bf16_f32 v14, v14, v15
	v_cvt_pk_bf16_f32 v15, v18, v19
	global_store_dwordx4 v[16:17], v[12:15], off
	s_branch .LBB0_1572

;     ...
;     for (int tile = first; tile < 8 * ncol_tiles; tile += stride) {
;         const int rt = tile & 7, ct = tile >> 3, r0 = MP_ROWS + 32 * rt, c0 = 32 * ct;
;         const bf16_t* ap = A + (size_t)(r0 + fr) * lda + (c0 >> 8) * a_grp_off + wid * kw + 8 * fq;
;         const bf16_t* bp = Bt + (size_t)(c0 + fr) * ldb + wid * kw + 8 * fq;
;         f32x4 acc[2][2];
; #pragma unroll
;         for (int i = 0; i < 2; ++i)
; #pragma unroll
;             for (int j = 0; j < 2; ++j) acc[i][j] = (f32x4){0.f, 0.f, 0.f, 0.f};
;         for (int s0 = 0; s0 < ksteps; s0 += 4) {
;             bf16x8 a0[4], a1[4], b0[4], b1[4];
; #pragma unroll
;             for (int j = 0; j < 4; ++j) if (s0 + j < ksteps) { const int s = s0 + j;
;                 a0[j] = *(const bf16x8*)(ap + 32 * s); a1[j] = *(const bf16x8*)(ap + (size_t)16 * lda + 32 * s);
;                 b0[j] = *(const bf16x8*)(bp + 32 * s); b1[j] = *(const bf16x8*)(bp + (size_t)16 * ldb + 32 * s); }
; #pragma unroll
;             for (int j = 0; j < 4; ++j) if (s0 + j < ksteps) {
;                 acc[0][0] = __builtin_amdgcn_mfma_f32_16x16x32_bf16(b0[j], a0[j], acc[0][0], 0, 0, 0); acc[0][1] = __builtin_amdgcn_mfma_f32_16x16x32_bf16(b1[j], a0[j], acc[0][1], 0, 0, 0);
;                 acc[1][0] = __builtin_amdgcn_mfma_f32_16x16x32_bf16(b0[j], a1[j], acc[1][0], 0, 0, 0); acc[1][1] = __builtin_amdgcn_mfma_f32_16x16x32_bf16(b1[j], a1[j], acc[1][1], 0, 0, 0); } }
; #pragma unroll
;         for (int i = 0; i < 2; ++i)
; #pragma unroll
;             for (int j = 0; j < 2; ++j) *(f32x4*)(part + (wid * 32 + 16 * i + fr) * 36 + 16 * j + 4 * fq) = acc[i][j];
.LBB0_1676:
	s_and_b32 s19, s3, 0xffffffe0
	s_and_b32 s10, s15, 0xe0
	v_or_b32_e32 v14, s19, v10
	s_bitset1_b32 s10, 14
	v_mad_i64_i32 v[70:71], s[12:13], v14, s17, v[4:5]
	v_or_b32_e32 v0, s10, v10
	v_mul_u32_u24_e32 v0, 0xb00, v0
	v_lshlrev_b32_e32 v0, 1, v0
	v_lshl_add_u64 v[72:73], v[2:3], 0, v[0:1]
	v_add_co_u32_e32 v74, vcc, 0x16000, v72
	v_addc_co_u32_e32 v75, vcc, 0, v73, vcc
	v_add_co_u32_e32 v76, vcc, 0x16000, v70
	v_addc_co_u32_e32 v77, vcc, 0, v71, vcc
	global_load_dwordx4 v[16:19], v[70:71], off
	global_load_dwordx4 v[20:23], v[72:73], off
	global_load_dwordx4 v[24:27], v[70:71], off offset:64
	global_load_dwordx4 v[28:31], v[74:75], off
	global_load_dwordx4 v[32:35], v[72:73], off offset:64
	global_load_dwordx4 v[36:39], v[72:73], off offset:640
	global_load_dwordx4 v[40:43], v[74:75], off offset:64
	global_load_dwordx4 v[44:47], v[70:71], off offset:128
	global_load_dwordx4 v[48:51], v[76:77], off
	global_load_dwordx4 v[52:55], v[74:75], off offset:640
	global_load_dwordx4 v[56:59], v[72:73], off offset:128
	global_load_dwordx4 v[60:63], v[72:73], off offset:192
	global_load_dwordx4 v[64:67], v[74:75], off offset:128
	global_load_dwordx4 v[78:81], v[74:75], off offset:192
	global_load_dwordx4 v[82:85], v[76:77], off offset:64
	global_load_dwordx4 v[86:89], v[76:77], off offset:128
	global_load_dwordx4 v[90:93], v[70:71], off offset:192
	global_load_dwordx4 v[94:97], v[70:71], off offset:256
	global_load_dwordx4 v[98:101], v[72:73], off offset:256
	global_load_dwordx4 v[102:105], v[72:73], off offset:320
	global_load_dwordx4 v[106:109], v[74:75], off offset:256
	global_load_dwordx4 v[110:113], v[74:75], off offset:320
	global_load_dwordx4 v[114:117], v[76:77], off offset:192
	global_load_dwordx4 v[118:121], v[76:77], off offset:256
	global_load_dwordx4 v[122:125], v[70:71], off offset:320
	global_load_dwordx4 v[126:129], v[70:71], off offset:384
	global_load_dwordx4 v[130:133], v[72:73], off offset:384
	global_load_dwordx4 v[134:137], v[72:73], off offset:448
	global_load_dwordx4 v[138:141], v[74:75], off offset:384
	global_load_dwordx4 v[142:145], v[74:75], off offset:448
	global_load_dwordx4 v[146:149], v[76:77], off offset:320
	global_load_dwordx4 v[150:153], v[76:77], off offset:384
	global_load_dwordx4 v[154:157], v[70:71], off offset:448
	global_load_dwordx4 v[158:161], v[70:71], off offset:512
	global_load_dwordx4 v[162:165], v[76:77], off offset:448
	global_load_dwordx4 v[166:169], v[76:77], off offset:512
	global_load_dwordx4 v[170:173], v[72:73], off offset:512
	global_load_dwordx4 v[174:177], v[72:73], off offset:576
	global_load_dwordx4 v[178:181], v[74:75], off offset:512
	global_load_dwordx4 v[182:185], v[70:71], off offset:576
	global_load_dwordx4 v[186:189], v[74:75], off offset:576
	global_load_dwordx4 v[190:193], v[76:77], off offset:576
	global_load_dwordx4 v[194:197], v[70:71], off offset:640
	global_load_dwordx4 v[198:201], v[76:77], off offset:640
	s_waitcnt vmcnt(42)
	v_mfma_f32_16x16x32_bf16 v[202:205], v[16:19], v[20:23], 0
	s_waitcnt vmcnt(40)
	v_mfma_f32_16x16x32_bf16 v[206:209], v[16:19], v[28:31], 0
	s_waitcnt vmcnt(39)
	v_mfma_f32_16x16x32_bf16 v[202:205], v[24:27], v[32:35], v[202:205]
	s_waitcnt vmcnt(37)
	v_mfma_f32_16x16x32_bf16 v[206:209], v[24:27], v[40:43], v[206:209]
	s_waitcnt vmcnt(35)
	v_mfma_f32_16x16x32_bf16 v[212:215], v[48:51], v[20:23], 0
	v_mfma_f32_16x16x32_bf16 v[216:219], v[48:51], v[28:31], 0
	s_waitcnt vmcnt(33)
	v_mfma_f32_16x16x32_bf16 v[202:205], v[44:47], v[56:59], v[202:205]
	s_waitcnt vmcnt(31)
	v_mfma_f32_16x16x32_bf16 v[206:209], v[44:47], v[64:67], v[206:209]
	s_waitcnt vmcnt(29)
	v_mfma_f32_16x16x32_bf16 v[212:215], v[82:85], v[32:35], v[212:215]
	v_mfma_f32_16x16x32_bf16 v[216:219], v[82:85], v[40:43], v[216:219]
	s_waitcnt vmcnt(28)
	v_mfma_f32_16x16x32_bf16 v[212:215], v[86:89], v[56:59], v[212:215]
	v_mfma_f32_16x16x32_bf16 v[216:219], v[86:89], v[64:67], v[216:219]
	s_waitcnt vmcnt(27)
	v_mfma_f32_16x16x32_bf16 v[202:205], v[90:93], v[60:63], v[202:205]
	v_mfma_f32_16x16x32_bf16 v[206:209], v[90:93], v[78:81], v[206:209]
	s_waitcnt vmcnt(25)
	v_mfma_f32_16x16x32_bf16 v[202:205], v[94:97], v[98:101], v[202:205]
	s_waitcnt vmcnt(23)
	v_mfma_f32_16x16x32_bf16 v[206:209], v[94:97], v[106:109], v[206:209]
	s_waitcnt vmcnt(21)
	v_mfma_f32_16x16x32_bf16 v[212:215], v[114:117], v[60:63], v[212:215]
	v_mfma_f32_16x16x32_bf16 v[216:219], v[114:117], v[78:81], v[216:219]
	s_waitcnt vmcnt(20)
	v_mfma_f32_16x16x32_bf16 v[212:215], v[118:121], v[98:101], v[212:215]
	v_mfma_f32_16x16x32_bf16 v[216:219], v[118:121], v[106:109], v[216:219]
	s_waitcnt vmcnt(19)
	v_mfma_f32_16x16x32_bf16 v[202:205], v[122:125], v[102:105], v[202:205]
	v_mfma_f32_16x16x32_bf16 v[206:209], v[122:125], v[110:113], v[206:209]
	s_waitcnt vmcnt(17)
	v_mfma_f32_16x16x32_bf16 v[202:205], v[126:129], v[130:133], v[202:205]
	s_waitcnt vmcnt(15)
	v_mfma_f32_16x16x32_bf16 v[206:209], v[126:129], v[138:141], v[206:209]
	s_waitcnt vmcnt(13)
	v_mfma_f32_16x16x32_bf16 v[212:215], v[146:149], v[102:105], v[212:215]
	v_mfma_f32_16x16x32_bf16 v[216:219], v[146:149], v[110:113], v[216:219]
	s_waitcnt vmcnt(12)
	v_mfma_f32_16x16x32_bf16 v[212:215], v[150:153], v[130:133], v[212:215]
	v_mfma_f32_16x16x32_bf16 v[216:219], v[150:153], v[138:141], v[216:219]
	s_waitcnt vmcnt(11)
	v_mfma_f32_16x16x32_bf16 v[202:205], v[154:157], v[134:137], v[202:205]
	s_waitcnt vmcnt(9)
	v_mfma_f32_16x16x32_bf16 v[212:215], v[162:165], v[134:137], v[212:215]
	v_mfma_f32_16x16x32_bf16 v[206:209], v[154:157], v[142:145], v[206:209]
	v_mfma_f32_16x16x32_bf16 v[216:219], v[162:165], v[142:145], v[216:219]
	s_waitcnt vmcnt(7)
	v_mfma_f32_16x16x32_bf16 v[202:205], v[158:161], v[170:173], v[202:205]
	v_mfma_f32_16x16x32_bf16 v[212:215], v[166:169], v[170:173], v[212:215]
	s_waitcnt vmcnt(5)
	v_mfma_f32_16x16x32_bf16 v[206:209], v[158:161], v[178:181], v[206:209]
	v_mfma_f32_16x16x32_bf16 v[216:219], v[166:169], v[178:181], v[216:219]
	s_waitcnt vmcnt(4)
	v_mfma_f32_16x16x32_bf16 v[202:205], v[182:185], v[174:177], v[202:205]
	s_waitcnt vmcnt(2)
	v_mfma_f32_16x16x32_bf16 v[212:215], v[190:193], v[174:177], v[212:215]
	v_mfma_f32_16x16x32_bf16 v[206:209], v[182:185], v[186:189], v[206:209]
	v_mfma_f32_16x16x32_bf16 v[216:219], v[190:193], v[186:189], v[216:219]
	s_waitcnt vmcnt(1)
	v_mfma_f32_16x16x32_bf16 v[202:205], v[194:197], v[36:39], v[202:205]
	s_waitcnt vmcnt(0)
	v_mfma_f32_16x16x32_bf16 v[212:215], v[198:201], v[36:39], v[212:215]
	v_mfma_f32_16x16x32_bf16 v[206:209], v[194:197], v[52:55], v[206:209]
	v_mfma_f32_16x16x32_bf16 v[216:219], v[198:201], v[52:55], v[216:219]
	s_nop 9
	ds_write_b128 v7, v[202:205]
	ds_write_b128 v7, v[212:215] offset:64
	ds_write_b128 v7, v[206:209] offset:2304
	ds_write_b128 v7, v[216:219] offset:2368
	s_waitcnt lgkmcnt(0)
	s_barrier
; __device__ __forceinline__ u32x4 pack8(const f32x4 a, const f32x4 b) { u32x4 w; w.x = cvt_pk_bf16(a[0], a[1]); w.y = cvt_pk_bf16(a[2], a[3]); w.z = cvt_pk_bf16(b[0], b[1]); w.w = cvt_pk_bf16(b[2], b[3]); return w; }
; __device__ __forceinline__ float sq8(const f32x4 a, const f32x4 b) { return (a[0] * a[0] + a[1] * a[1]) + (a[2] * a[2] + a[3] * a[3]) + (b[0] * b[0] + b[1] * b[1]) + (b[2] * b[2] + b[3] * b[3]); }
;     __device__ __forceinline__ float apply8(int r, int c, const f32x4 a0, const f32x4 a1) const { *(u32x4*)(O + (size_t)r * ldc + c) = pack8(a0, a1); return 0.f; }
;     __device__ __forceinline__ float apply8(int r, int c, const f32x4 a0, const f32x4 a1) const {
;         float* hp = h + (size_t)r * D + c; const f32x4 v0 = *(const f32x4*)hp + a0 * mul, v1 = *(const f32x4*)(hp + 4) + a1 * mul;
;         *(f32x4*)hp = v0; *(f32x4*)(hp + 4) = v1; *(u32x4*)(hb + (size_t)r * D + c) = pack8(v0, v1); return sq8(v0, v1); }
;     ...
;         if (tid < 128) { const int row = tid >> 2, oct = tid & 3; f32x4 v0 = (f32x4){0.f, 0.f, 0.f, 0.f}, v1 = v0;
; #pragma unroll
;             for (int w = 0; w < 8; ++w) { v0 += *(const f32x4*)(part + (w * 32 + row) * 36 + 8 * oct); v1 += *(const f32x4*)(part + (w * 32 + row) * 36 + 8 * oct + 4); }
;             float sq = E.apply8(r0 + row, c0 + 8 * oct, v0, v1);
;             if (Epi::HAS_SSQ) { sq += __shfl_xor(sq, 1); sq += __shfl_xor(sq, 2); if (oct == 0) atomicAdd(E.ssq + r0 + row, sq); } }
	s_and_saveexec_b64 s[12:13], s[6:7]
	s_cbranch_execz .LBB0_1675
	v_add_u32_e32 v86, s10, v6
	v_ashrrev_i32_e32 v87, 31, v86
	v_or_b32_e32 v88, s19, v11
	v_lshlrev_b64 v[14:15], 12, v[86:87]
	v_lshl_add_u64 v[14:15], s[52:53], 0, v[14:15]
	v_ashrrev_i32_e32 v89, 31, v88
	v_lshl_add_u64 v[90:91], v[88:89], 2, v[14:15]
	global_load_dwordx4 v[14:17], v[90:91], off
	global_load_dwordx4 v[18:21], v[90:91], off offset:16
	ds_read_b128 v[22:25], v12
	ds_read_b128 v[26:29], v12 offset:16
	ds_read_b128 v[30:33], v12 offset:4608
	ds_read_b128 v[34:37], v12 offset:4624
	ds_read_b128 v[38:41], v12 offset:9216
	ds_read_b128 v[42:45], v12 offset:9232
	ds_read_b128 v[46:49], v12 offset:13824
	ds_read_b128 v[50:53], v12 offset:13840
	ds_read_b128 v[54:57], v12 offset:18432
	ds_read_b128 v[58:61], v12 offset:18448
	ds_read_b128 v[62:65], v12 offset:23040
	ds_read_b128 v[66:69], v12 offset:23056
	ds_read_b128 v[70:73], v12 offset:27648
	ds_read_b128 v[74:77], v12 offset:27664
	ds_read_b128 v[78:81], v12 offset:32256
	ds_read_b128 v[82:85], v12 offset:32272
	s_waitcnt lgkmcnt(14)
	v_pk_add_f32 v[24:25], v[24:25], 0 op_sel_hi:[1,0]
	v_pk_add_f32 v[22:23], v[22:23], 0 op_sel_hi:[1,0]
	v_pk_add_f32 v[26:27], v[26:27], 0 op_sel_hi:[1,0]
	s_waitcnt lgkmcnt(13)
	v_pk_add_f32 v[24:25], v[24:25], v[32:33]
	v_pk_add_f32 v[22:23], v[22:23], v[30:31]
	v_pk_add_f32 v[28:29], v[28:29], 0 op_sel_hi:[1,0]
	s_waitcnt lgkmcnt(12)
	v_pk_add_f32 v[26:27], v[26:27], v[34:35]
	s_waitcnt lgkmcnt(11)
	v_pk_add_f32 v[24:25], v[24:25], v[40:41]
	v_pk_add_f32 v[22:23], v[22:23], v[38:39]
	v_pk_add_f32 v[28:29], v[28:29], v[36:37]
	s_waitcnt lgkmcnt(10)
	v_pk_add_f32 v[26:27], v[26:27], v[42:43]
	s_waitcnt lgkmcnt(9)
	v_pk_add_f32 v[24:25], v[24:25], v[48:49]
	v_pk_add_f32 v[22:23], v[22:23], v[46:47]
	v_pk_add_f32 v[28:29], v[28:29], v[44:45]
	s_waitcnt lgkmcnt(8)
	v_pk_add_f32 v[26:27], v[26:27], v[50:51]
	s_waitcnt lgkmcnt(7)
	v_pk_add_f32 v[24:25], v[24:25], v[56:57]
	v_pk_add_f32 v[22:23], v[22:23], v[54:55]
	v_pk_add_f32 v[28:29], v[28:29], v[52:53]
	s_waitcnt lgkmcnt(6)
	v_pk_add_f32 v[26:27], v[26:27], v[58:59]
	s_waitcnt lgkmcnt(5)
	v_pk_add_f32 v[24:25], v[24:25], v[64:65]
	v_pk_add_f32 v[22:23], v[22:23], v[62:63]
	v_pk_add_f32 v[28:29], v[28:29], v[60:61]
	s_waitcnt lgkmcnt(4)
	v_pk_add_f32 v[26:27], v[26:27], v[66:67]
	s_waitcnt lgkmcnt(3)
	v_pk_add_f32 v[24:25], v[24:25], v[72:73]
	v_pk_add_f32 v[22:23], v[22:23], v[70:71]
	v_pk_add_f32 v[28:29], v[28:29], v[68:69]
	s_waitcnt lgkmcnt(2)
	v_pk_add_f32 v[26:27], v[26:27], v[74:75]
	s_waitcnt lgkmcnt(1)
	v_pk_add_f32 v[24:25], v[24:25], v[80:81]
	v_pk_add_f32 v[22:23], v[22:23], v[78:79]
	v_pk_add_f32 v[28:29], v[28:29], v[76:77]
	s_waitcnt lgkmcnt(0)
	v_pk_add_f32 v[26:27], v[26:27], v[82:83]
	v_and_b32_e32 v92, 64, v13
	v_pk_add_f32 v[28:29], v[28:29], v[84:85]
	v_xor_b32_e32 v0, 1, v13
	v_add_u32_e32 v92, 64, v92
	v_cmp_lt_i32_e32 vcc, v0, v92
	v_xor_b32_e32 v93, 2, v13
	s_waitcnt vmcnt(1)
	v_pk_add_f32 v[16:17], v[24:25], v[16:17]
	v_pk_add_f32 v[14:15], v[22:23], v[14:15]
	s_waitcnt vmcnt(0)
	v_pk_add_f32 v[18:19], v[26:27], v[18:19]
	v_mul_f32_e32 v22, v15, v15
	v_mul_f32_e32 v23, v17, v17
	v_pk_add_f32 v[20:21], v[28:29], v[20:21]
	v_mul_f32_e32 v24, v19, v19
	v_fmac_f32_e32 v22, v14, v14
	v_fmac_f32_e32 v23, v16, v16
	v_mul_f32_e32 v25, v21, v21
	v_fmac_f32_e32 v24, v18, v18
	v_add_f32_e32 v22, v22, v23
	v_cndmask_b32_e32 v0, v13, v0, vcc
	v_fmac_f32_e32 v25, v20, v20
	v_add_f32_e32 v22, v24, v22
	v_lshlrev_b32_e32 v0, 2, v0
	v_add_f32_e32 v26, v25, v22
	ds_bpermute_b32 v0, v0, v26
	v_cmp_lt_i32_e32 vcc, v93, v92
	global_store_dwordx4 v[90:91], v[14:17], off
	global_store_dwordx4 v[90:91], v[18:21], off offset:16
	v_cndmask_b32_e32 v92, v13, v93, vcc
	v_cvt_pk_bf16_f32 v22, v14, v15
	s_waitcnt lgkmcnt(0)
	v_add_f32_e32 v0, v26, v0
	v_lshlrev_b32_e32 v14, 2, v92
	ds_bpermute_b32 v14, v14, v0
	v_cvt_pk_bf16_f32 v23, v16, v17
	v_lshlrev_b64 v[16:17], 11, v[86:87]
	v_lshl_add_u64 v[16:17], s[68:69], 0, v[16:17]
	v_lshl_add_u64 v[16:17], v[88:89], 1, v[16:17]
	v_cvt_pk_bf16_f32 v24, v18, v19
	v_cvt_pk_bf16_f32 v25, v20, v21
	global_store_dwordx4 v[16:17], v[22:25], off
	s_and_b64 exec, exec, s[8:9]
	s_cbranch_execz .LBB0_1675
	s_lshl_b32 s10, s10, 2
	v_lshl_add_u64 v[16:17], v[8:9], 0, s[10:11]
	s_waitcnt lgkmcnt(0)
	v_add_f32_e32 v0, v0, v14
	global_atomic_add_f32 v[16:17], v0, off
	s_branch .LBB0_1675

;     ...
;     for (int tile = first; tile < 8 * ncol_tiles; tile += stride) {
;         const int rt = tile & 7, ct = tile >> 3, r0 = MP_ROWS + 32 * rt, c0 = 32 * ct;
;         const bf16_t* ap = A + (size_t)(r0 + fr) * lda + (c0 >> 8) * a_grp_off + wid * kw + 8 * fq;
;         const bf16_t* bp = Bt + (size_t)(c0 + fr) * ldb + wid * kw + 8 * fq;
;         f32x4 acc[2][2];
; #pragma unroll
;         for (int i = 0; i < 2; ++i)
; #pragma unroll
;             for (int j = 0; j < 2; ++j) acc[i][j] = (f32x4){0.f, 0.f, 0.f, 0.f};
;         for (int s0 = 0; s0 < ksteps; s0 += 4) {
;             bf16x8 a0[4], a1[4], b0[4], b1[4];
; #pragma unroll
;             for (int j = 0; j < 4; ++j) if (s0 + j < ksteps) { const int s = s0 + j;
;                 a0[j] = *(const bf16x8*)(ap + 32 * s); a1[j] = *(const bf16x8*)(ap + (size_t)16 * lda + 32 * s);
;                 b0[j] = *(const bf16x8*)(bp + 32 * s); b1[j] = *(const bf16x8*)(bp + (size_t)16 * ldb + 32 * s); }
; #pragma unroll
;             for (int j = 0; j < 4; ++j) if (s0 + j < ksteps) {
;                 acc[0][0] = __builtin_amdgcn_mfma_f32_16x16x32_bf16(b0[j], a0[j], acc[0][0], 0, 0, 0); acc[0][1] = __builtin_amdgcn_mfma_f32_16x16x32_bf16(b1[j], a0[j], acc[0][1], 0, 0, 0);
;                 acc[1][0] = __builtin_amdgcn_mfma_f32_16x16x32_bf16(b0[j], a1[j], acc[1][0], 0, 0, 0); acc[1][1] = __builtin_amdgcn_mfma_f32_16x16x32_bf16(b1[j], a1[j], acc[1][1], 0, 0, 0); } }
; #pragma unroll
;         for (int i = 0; i < 2; ++i)
; #pragma unroll
;             for (int j = 0; j < 2; ++j) *(f32x4*)(part + (wid * 32 + 16 * i + fr) * 36 + 16 * j + 4 * fq) = acc[i][j];
;         __syncthreads();
.LBB0_1776:
	s_and_b32 s22, s3, 0xffffffe0
	v_or_b32_e32 v16, s22, v10
	v_ashrrev_i32_e32 v17, 31, v16
	v_lshlrev_b64 v[16:17], 11, v[16:17]
	s_and_b32 s10, s17, 0xe0
	v_lshl_add_u64 v[52:53], v[4:5], 0, v[16:17]
	s_bitset1_b32 s10, 14
	v_or_b32_e32 v0, s10, v10
	v_lshlrev_b32_e32 v0, 11, v0
	v_lshl_add_u64 v[54:55], v[2:3], 0, v[0:1]
	v_add_co_u32_e32 v60, vcc, s19, v54
	v_addc_co_u32_e32 v61, vcc, 0, v55, vcc
	v_add_co_u32_e32 v62, vcc, s19, v52
	v_addc_co_u32_e32 v63, vcc, 0, v53, vcc
	global_load_dwordx4 v[18:21], v[52:53], off
	global_load_dwordx4 v[22:25], v[54:55], off
	global_load_dwordx4 v[26:29], v[60:61], off
	global_load_dwordx4 v[30:33], v[54:55], off offset:64
	global_load_dwordx4 v[34:37], v[52:53], off offset:64
	global_load_dwordx4 v[38:41], v[62:63], off
	global_load_dwordx4 v[42:45], v[60:61], off offset:64
	global_load_dwordx4 v[46:49], v[62:63], off offset:64
	global_load_dwordx4 v[56:59], v[52:53], off offset:128
	global_load_dwordx4 v[64:67], v[54:55], off offset:128
	global_load_dwordx4 v[68:71], v[60:61], off offset:128
	global_load_dwordx4 v[72:75], v[54:55], off offset:192
	global_load_dwordx4 v[76:79], v[52:53], off offset:192
	global_load_dwordx4 v[80:83], v[62:63], off offset:128
	global_load_dwordx4 v[84:87], v[60:61], off offset:192
	global_load_dwordx4 v[88:91], v[62:63], off offset:192
	s_waitcnt vmcnt(14)
	v_mfma_f32_16x16x32_bf16 v[92:95], v[18:21], v[22:25], 0
	s_waitcnt vmcnt(13)
	v_mfma_f32_16x16x32_bf16 v[96:99], v[18:21], v[26:29], 0
	s_waitcnt vmcnt(10)
	v_mfma_f32_16x16x32_bf16 v[100:103], v[38:41], v[22:25], 0
	v_mfma_f32_16x16x32_bf16 v[92:95], v[34:37], v[30:33], v[92:95]
	s_waitcnt vmcnt(9)
	v_mfma_f32_16x16x32_bf16 v[96:99], v[34:37], v[42:45], v[96:99]
	v_mfma_f32_16x16x32_bf16 v[104:107], v[38:41], v[26:29], 0
	s_waitcnt vmcnt(8)
	v_mfma_f32_16x16x32_bf16 v[100:103], v[46:49], v[30:33], v[100:103]
	v_mfma_f32_16x16x32_bf16 v[104:107], v[46:49], v[42:45], v[104:107]
	s_waitcnt vmcnt(6)
	v_mfma_f32_16x16x32_bf16 v[92:95], v[56:59], v[64:67], v[92:95]
	s_waitcnt vmcnt(5)
	v_mfma_f32_16x16x32_bf16 v[96:99], v[56:59], v[68:71], v[96:99]
	s_waitcnt vmcnt(2)
	v_mfma_f32_16x16x32_bf16 v[100:103], v[80:83], v[64:67], v[100:103]
	v_mfma_f32_16x16x32_bf16 v[104:107], v[80:83], v[68:71], v[104:107]
	v_mfma_f32_16x16x32_bf16 v[92:95], v[76:79], v[72:75], v[92:95]
	s_waitcnt vmcnt(1)
	v_mfma_f32_16x16x32_bf16 v[96:99], v[76:79], v[84:87], v[96:99]
	s_waitcnt vmcnt(0)
	v_mfma_f32_16x16x32_bf16 v[100:103], v[88:91], v[72:75], v[100:103]
	v_mfma_f32_16x16x32_bf16 v[104:107], v[88:91], v[84:87], v[104:107]
	s_nop 9
	ds_write_b128 v7, v[92:95]
	ds_write_b128 v7, v[96:99] offset:2304
	ds_write_b128 v7, v[100:103] offset:64
	ds_write_b128 v7, v[104:107] offset:2368
	s_waitcnt lgkmcnt(0)
	s_barrier
	s_and_saveexec_b64 s[12:13], s[6:7]
	s_cbranch_execz .LBB0_1775
; __device__ __forceinline__ float bf_lo(unsigned w) { return __uint_as_float(w << 16); }
; __device__ __forceinline__ float bf_hi(unsigned w) { return __uint_as_float(w & 0xffff0000u); }
; __device__ __forceinline__ float sigmoidf_(float x) { return __builtin_amdgcn_rcpf(1.0f + __expf(-x)); }
; __device__ __forceinline__ float rinv_of(float ssq) { return rsqrtf(ssq * (1.0f / 1024.0f) + EPS); }
; __device__ __forceinline__ u32x4 pack8(const f32x4 a, const f32x4 b) { u32x4 w; w.x = cvt_pk_bf16(a[0], a[1]); w.y = cvt_pk_bf16(a[2], a[3]); w.z = cvt_pk_bf16(b[0], b[1]); w.w = cvt_pk_bf16(b[2], b[3]); return w; }
; __device__ __forceinline__ float sq8(const f32x4 a, const f32x4 b) { return (a[0] * a[0] + a[1] * a[1]) + (a[2] * a[2] + a[3] * a[3]) + (b[0] * b[0] + b[1] * b[1]) + (b[2] * b[2] + b[3] * b[3]); }
;     __device__ __forceinline__ float apply8(int r, int c, const f32x4 a0_, const f32x4 a1_) const {
;         const float ri = rinv_of(ssq_in[r]); float* hp = h + (size_t)r * D + c; const u32x4 pw = *(const u32x4*)(pp + (size_t)r * D + c);
;         const f32x4 a0 = a0_ * ri, a1 = a1_ * ri; f32x4 v0 = *(const f32x4*)hp, v1 = *(const f32x4*)(hp + 4);
;         if (mul == 0.f) { if (hb) *(u32x4*)(hb + (size_t)r * D + c) = pack8(v0, v1); return 0.f; }
;         v0[0] += sigmoidf_(a0[0]) * bf_lo(pw.x); v0[1] += sigmoidf_(a0[1]) * bf_hi(pw.x); v0[2] += sigmoidf_(a0[2]) * bf_lo(pw.y); v0[3] += sigmoidf_(a0[3]) * bf_hi(pw.y);
;         v1[0] += sigmoidf_(a1[0]) * bf_lo(pw.z); v1[1] += sigmoidf_(a1[1]) * bf_hi(pw.z); v1[2] += sigmoidf_(a1[2]) * bf_lo(pw.w); v1[3] += sigmoidf_(a1[3]) * bf_hi(pw.w);
;         *(f32x4*)hp = v0; *(f32x4*)(hp + 4) = v1; if (hb) *(u32x4*)(hb + (size_t)r * D + c) = pack8(v0, v1); return sq8(v0, v1); }
;     ...
;         if (tid < 128) { const int row = tid >> 2, oct = tid & 3; f32x4 v0 = (f32x4){0.f, 0.f, 0.f, 0.f}, v1 = v0;
; #pragma unroll
;             for (int w = 0; w < 8; ++w) { v0 += *(const f32x4*)(part + (w * 32 + row) * 36 + 8 * oct); v1 += *(const f32x4*)(part + (w * 32 + row) * 36 + 8 * oct + 4); }
;             float sq = E.apply8(r0 + row, c0 + 8 * oct, v0, v1);
;             if (Epi::HAS_SSQ) { sq += __shfl_xor(sq, 1); sq += __shfl_xor(sq, 2); if (oct == 0) atomicAdd(E.ssq + r0 + row, sq); } }
	v_add_u32_e32 v44, s10, v6
	v_ashrrev_i32_e32 v45, 31, v44
	v_lshl_add_u64 v[16:17], v[44:45], 2, s[14:15]
	global_load_dword v0, v[16:17], off
	v_or_b32_e32 v46, s22, v11
	v_ashrrev_i32_e32 v47, 31, v46
	v_lshlrev_b64 v[92:93], 11, v[44:45]
	v_lshl_add_u64 v[16:17], s[72:73], 0, v[92:93]
	v_lshlrev_b64 v[94:95], 1, v[46:47]
	v_lshlrev_b64 v[44:45], 12, v[44:45]
	v_lshl_add_u64 v[16:17], v[16:17], 0, v[94:95]
	v_lshl_add_u64 v[44:45], s[52:53], 0, v[44:45]
	global_load_dwordx4 v[16:19], v[16:17], off
	v_lshl_add_u64 v[96:97], v[46:47], 2, v[44:45]
	ds_read_b128 v[20:23], v12
	ds_read_b128 v[24:27], v12 offset:16
	ds_read_b128 v[28:31], v12 offset:4624
	ds_read_b128 v[32:35], v12 offset:4608
	ds_read_b128 v[36:39], v12 offset:9232
	ds_read_b128 v[40:43], v12 offset:9216
	global_load_dwordx4 v[44:47], v[96:97], off offset:16
	global_load_dwordx4 v[48:51], v[96:97], off
	s_waitcnt lgkmcnt(5)
	v_pk_add_f32 v[20:21], v[20:21], 0 op_sel_hi:[1,0]
	s_waitcnt lgkmcnt(4)
	v_pk_add_f32 v[26:27], v[26:27], 0 op_sel_hi:[1,0]
	v_pk_add_f32 v[24:25], v[24:25], 0 op_sel_hi:[1,0]
	v_pk_add_f32 v[22:23], v[22:23], 0 op_sel_hi:[1,0]
	s_waitcnt lgkmcnt(2)
	v_pk_add_f32 v[20:21], v[20:21], v[32:33]
	ds_read_b128 v[52:55], v12 offset:13840
	ds_read_b128 v[56:59], v12 offset:13824
	ds_read_b128 v[60:63], v12 offset:18448
	ds_read_b128 v[64:67], v12 offset:18432
	ds_read_b128 v[68:71], v12 offset:23056
	ds_read_b128 v[72:75], v12 offset:23040
	ds_read_b128 v[76:79], v12 offset:27664
	ds_read_b128 v[80:83], v12 offset:27648
	ds_read_b128 v[84:87], v12 offset:32272
	ds_read_b128 v[88:91], v12 offset:32256
	v_pk_add_f32 v[26:27], v[26:27], v[30:31]
	v_pk_add_f32 v[24:25], v[24:25], v[28:29]
	v_pk_add_f32 v[22:23], v[22:23], v[34:35]
	s_waitcnt lgkmcnt(10)
	v_pk_add_f32 v[20:21], v[20:21], v[40:41]
	v_pk_add_f32 v[26:27], v[26:27], v[38:39]
	v_pk_add_f32 v[24:25], v[24:25], v[36:37]
	v_pk_add_f32 v[22:23], v[22:23], v[42:43]
	s_waitcnt lgkmcnt(8)
	v_pk_add_f32 v[20:21], v[20:21], v[56:57]
	v_pk_add_f32 v[26:27], v[26:27], v[54:55]
	v_pk_add_f32 v[24:25], v[24:25], v[52:53]
	v_pk_add_f32 v[22:23], v[22:23], v[58:59]
	s_waitcnt lgkmcnt(6)
	v_pk_add_f32 v[20:21], v[20:21], v[64:65]
	v_pk_add_f32 v[26:27], v[26:27], v[62:63]
	v_pk_add_f32 v[24:25], v[24:25], v[60:61]
	v_pk_add_f32 v[22:23], v[22:23], v[66:67]
	s_waitcnt lgkmcnt(4)
	v_pk_add_f32 v[20:21], v[20:21], v[72:73]
	v_pk_add_f32 v[26:27], v[26:27], v[70:71]
	v_pk_add_f32 v[24:25], v[24:25], v[68:69]
	v_pk_add_f32 v[22:23], v[22:23], v[74:75]
	s_waitcnt lgkmcnt(2)
	v_pk_add_f32 v[20:21], v[20:21], v[80:81]
	v_pk_add_f32 v[26:27], v[26:27], v[78:79]
	v_pk_add_f32 v[24:25], v[24:25], v[76:77]
	v_pk_add_f32 v[22:23], v[22:23], v[82:83]
	s_waitcnt lgkmcnt(0)
	v_pk_add_f32 v[20:21], v[20:21], v[88:89]
	v_pk_add_f32 v[26:27], v[26:27], v[86:87]
	v_pk_add_f32 v[24:25], v[24:25], v[84:85]
	v_pk_add_f32 v[22:23], v[22:23], v[90:91]
	s_waitcnt vmcnt(3)
	v_fmamk_f32 v0, v0, 0x3a800000, v13
	v_mul_f32_e32 v15, 0x4b800000, v0
	v_cmp_gt_f32_e32 vcc, s20, v0
	s_waitcnt vmcnt(2)
	v_lshlrev_b32_e32 v28, 16, v16
	v_cndmask_b32_e32 v0, v0, v15, vcc
	v_rsq_f32_e32 v0, v0
	v_and_b32_e32 v29, 0xffff0000, v16
	v_lshlrev_b32_e32 v16, 16, v17
	v_and_b32_e32 v17, 0xffff0000, v17
	v_mul_f32_e32 v15, 0x45800000, v0
	v_cndmask_b32_e32 v0, v0, v15, vcc
	v_pk_mul_f32 v[20:21], v[20:21], v[0:1] op_sel_hi:[1,0]
	v_pk_mul_f32 v[26:27], v[26:27], v[0:1] op_sel_hi:[1,0]
	v_pk_mul_f32 v[24:25], v[24:25], v[0:1] op_sel_hi:[1,0]
	v_pk_mul_f32 v[22:23], v[22:23], v[0:1] op_sel_hi:[1,0]
	v_mul_f32_e32 v0, 0xbfb8aa3b, v20
	v_mul_f32_e32 v15, 0xbfb8aa3b, v21
	v_mul_f32_e32 v20, 0xbfb8aa3b, v22
	v_mul_f32_e32 v21, 0xbfb8aa3b, v23
	v_mul_f32_e32 v23, 0xbfb8aa3b, v25
	v_exp_f32_e32 v0, v0
	v_mul_f32_e32 v22, 0xbfb8aa3b, v24
	v_exp_f32_e32 v20, v20
	v_exp_f32_e32 v21, v21
	v_exp_f32_e32 v24, v23
	v_exp_f32_e32 v15, v15
	v_exp_f32_e32 v22, v22
	v_add_f32_e32 v0, 1.0, v0
	v_add_f32_e32 v23, 1.0, v20
	v_add_f32_e32 v25, 1.0, v21
	v_rcp_f32_e32 v20, v0
	v_add_f32_e32 v0, 1.0, v24
	v_add_f32_e32 v15, 1.0, v15
	v_add_f32_e32 v30, 1.0, v22
	v_rcp_f32_e32 v22, v23
	v_rcp_f32_e32 v23, v25
	v_rcp_f32_e32 v25, v0
	v_mul_f32_e32 v0, 0xbfb8aa3b, v26
	v_rcp_f32_e32 v21, v15
	v_exp_f32_e32 v0, v0
	v_mul_f32_e32 v15, 0xbfb8aa3b, v27
	v_exp_f32_e32 v15, v15
	v_rcp_f32_e32 v24, v30
	v_add_f32_e32 v0, 1.0, v0
	v_rcp_f32_e32 v26, v0
	v_add_f32_e32 v0, 1.0, v15
	v_rcp_f32_e32 v27, v0
	s_waitcnt vmcnt(0)
	v_pk_fma_f32 v[20:21], v[20:21], v[28:29], v[48:49]
	v_pk_fma_f32 v[22:23], v[22:23], v[16:17], v[50:51]
	v_lshlrev_b32_e32 v16, 16, v18
	v_and_b32_e32 v17, 0xffff0000, v18
	v_lshlrev_b32_e32 v18, 16, v19
	v_and_b32_e32 v19, 0xffff0000, v19
	v_pk_fma_f32 v[16:17], v[24:25], v[16:17], v[44:45]
	v_pk_fma_f32 v[18:19], v[26:27], v[18:19], v[46:47]
	v_pk_mul_f32 v[24:25], v[20:21], v[20:21]
	v_pk_mul_f32 v[26:27], v[22:23], v[22:23]
	v_pk_mul_f32 v[28:29], v[16:17], v[16:17]
	v_add_f32_e32 v0, v26, v27
	v_add_f32_e32 v15, v24, v25
	v_pk_mul_f32 v[30:31], v[18:19], v[18:19]
	v_add_f32_e32 v0, v15, v0
	v_add_f32_e32 v15, v28, v29
	v_add_f32_e32 v0, v15, v0
	v_add_f32_e32 v15, v30, v31
	v_and_b32_e32 v24, 64, v14
	v_add_f32_e32 v0, v15, v0
	v_xor_b32_e32 v15, 1, v14
	v_add_u32_e32 v24, 64, v24
	v_cmp_lt_i32_e32 vcc, v15, v24
	global_store_dwordx4 v[96:97], v[20:23], off
	global_store_dwordx4 v[96:97], v[16:19], off offset:16
	v_cndmask_b32_e32 v15, v14, v15, vcc
	v_lshlrev_b32_e32 v15, 2, v15
	ds_bpermute_b32 v15, v15, v0
	v_cvt_pk_bf16_f32 v20, v20, v21
	v_cvt_pk_bf16_f32 v21, v22, v23
	v_cvt_pk_bf16_f32 v22, v16, v17
	v_lshl_add_u64 v[16:17], s[70:71], 0, v[92:93]
	s_waitcnt lgkmcnt(0)
	v_add_f32_e32 v0, v0, v15
	v_xor_b32_e32 v15, 2, v14
	v_cmp_lt_i32_e32 vcc, v15, v24
	v_lshl_add_u64 v[16:17], v[16:17], 0, v[94:95]
	v_cvt_pk_bf16_f32 v23, v18, v19
	global_store_dwordx4 v[16:17], v[20:23], off
	v_cndmask_b32_e32 v15, v14, v15, vcc
	v_lshlrev_b32_e32 v15, 2, v15
	ds_bpermute_b32 v15, v15, v0
	s_and_b64 exec, exec, s[8:9]
	s_cbranch_execz .LBB0_1775
	s_lshl_b32 s10, s10, 2
	v_lshl_add_u64 v[16:17], v[8:9], 0, s[10:11]
	s_waitcnt lgkmcnt(0)
	v_add_f32_e32 v0, v0, v15
	global_atomic_add_f32 v[16:17], v0, off
	s_branch .LBB0_1775

; __device__ __forceinline__ float rinv_of(float ssq) { return rsqrtf(ssq * (1.0f / 1024.0f) + EPS); }
; __device__ __forceinline__ u32x4 pack8(const f32x4 a, const f32x4 b) { u32x4 w; w.x = cvt_pk_bf16(a[0], a[1]); w.y = cvt_pk_bf16(a[2], a[3]); w.z = cvt_pk_bf16(b[0], b[1]); w.w = cvt_pk_bf16(b[2], b[3]); return w; }
;     __device__ __forceinline__ float apply8(int r, int c, const f32x4 a0, const f32x4 a1) const { *(u32x4*)(O + (size_t)r * ldc + c) = pack8(a0, a1); return 0.f; }
;     __device__ __forceinline__ float apply8(int r, int c, const f32x4 a0, const f32x4 a1) const {
;         bf16_t* base; int ldc, cc; float sc = 1.0f;
;         if (c < 512) { base = q; ldc = KEYD; cc = c; sc = 0.08838834764831845f; } else if (c < 1024) { base = k; ldc = KEYD; cc = c - 512; } else { base = g; ldc = D; cc = c - 1024; }
;         const float ri = rinv_of(ssq_in[r]) * sc; *(u32x4*)(base + (size_t)r * ldc + cc) = pack8(a0 * ri, a1 * ri); return 0.f; }
;     ...
;         for (int s0 = 0; s0 < ksteps; s0 += 4) {
;             bf16x8 a0[4], a1[4], b0[4], b1[4];
; #pragma unroll
;             for (int j = 0; j < 4; ++j) if (s0 + j < ksteps) { const int s = s0 + j;
;                 a0[j] = *(const bf16x8*)(ap + 32 * s); a1[j] = *(const bf16x8*)(ap + (size_t)16 * lda + 32 * s);
;                 b0[j] = *(const bf16x8*)(bp + 32 * s); b1[j] = *(const bf16x8*)(bp + (size_t)16 * ldb + 32 * s); }
; #pragma unroll
;             for (int j = 0; j < 4; ++j) if (s0 + j < ksteps) {
;                 acc[0][0] = __builtin_amdgcn_mfma_f32_16x16x32_bf16(b0[j], a0[j], acc[0][0], 0, 0, 0); acc[0][1] = __builtin_amdgcn_mfma_f32_16x16x32_bf16(b1[j], a0[j], acc[0][1], 0, 0, 0);
;                 acc[1][0] = __builtin_amdgcn_mfma_f32_16x16x32_bf16(b0[j], a1[j], acc[1][0], 0, 0, 0); acc[1][1] = __builtin_amdgcn_mfma_f32_16x16x32_bf16(b1[j], a1[j], acc[1][1], 0, 0, 0); } }
; #pragma unroll
;         for (int i = 0; i < 2; ++i)
; #pragma unroll
;             for (int j = 0; j < 2; ++j) *(f32x4*)(part + (wid * 32 + 16 * i + fr) * 36 + 16 * j + 4 * fq) = acc[i][j];
;         __syncthreads();
;         if (tid < 128) { const int row = tid >> 2, oct = tid & 3; f32x4 v0 = (f32x4){0.f, 0.f, 0.f, 0.f}, v1 = v0;
; #pragma unroll
;             for (int w = 0; w < 8; ++w) { v0 += *(const f32x4*)(part + (w * 32 + row) * 36 + 8 * oct); v1 += *(const f32x4*)(part + (w * 32 + row) * 36 + 8 * oct + 4); }
.LBB0_1872:
	s_and_b32 s12, s3, 0xffffffe0
	v_or_b32_e32 v0, s12, v76
	v_ashrrev_i32_e32 v1, 31, v0
	v_lshlrev_b64 v[0:1], 11, v[0:1]
	s_and_b32 s25, s19, 0xe0
	v_lshl_add_u64 v[36:37], v[68:69], 0, v[0:1]
	s_bitset1_b32 s25, 14
	v_or_b32_e32 v4, s25, v76
	v_lshlrev_b32_e32 v64, 11, v4
	v_lshl_add_u64 v[38:39], v[66:67], 0, v[64:65]
	v_add_co_u32_e32 v44, vcc, s21, v38
	v_addc_co_u32_e32 v45, vcc, 0, v39, vcc
	v_add_co_u32_e32 v46, vcc, s21, v36
	v_addc_co_u32_e32 v47, vcc, 0, v37, vcc
	global_load_dwordx4 v[6:9], v[36:37], off
	global_load_dwordx4 v[10:13], v[38:39], off
	global_load_dwordx4 v[14:17], v[44:45], off
	global_load_dwordx4 v[18:21], v[38:39], off offset:64
	global_load_dwordx4 v[22:25], v[36:37], off offset:64
	global_load_dwordx4 v[26:29], v[46:47], off
	global_load_dwordx4 v[30:33], v[44:45], off offset:64
	global_load_dwordx4 v[40:43], v[46:47], off offset:64
	global_load_dwordx4 v[48:51], v[36:37], off offset:128
	global_load_dwordx4 v[52:55], v[38:39], off offset:128
	global_load_dwordx4 v[56:59], v[44:45], off offset:128
	global_load_dwordx4 v[60:63], v[38:39], off offset:192
	global_load_dwordx4 v[70:73], v[36:37], off offset:192
	global_load_dwordx4 v[82:85], v[46:47], off offset:128
	global_load_dwordx4 v[86:89], v[44:45], off offset:192
	global_load_dwordx4 v[90:93], v[46:47], off offset:192
	s_waitcnt vmcnt(14)
	v_mfma_f32_16x16x32_bf16 v[94:97], v[6:9], v[10:13], 0
	s_waitcnt vmcnt(13)
	v_mfma_f32_16x16x32_bf16 v[98:101], v[6:9], v[14:17], 0
	s_waitcnt vmcnt(10)
	v_mfma_f32_16x16x32_bf16 v[102:105], v[26:29], v[10:13], 0
	v_mfma_f32_16x16x32_bf16 v[94:97], v[22:25], v[18:21], v[94:97]
	s_waitcnt vmcnt(9)
	v_mfma_f32_16x16x32_bf16 v[98:101], v[22:25], v[30:33], v[98:101]
	v_mfma_f32_16x16x32_bf16 v[106:109], v[26:29], v[14:17], 0
	s_waitcnt vmcnt(8)
	v_mfma_f32_16x16x32_bf16 v[102:105], v[40:43], v[18:21], v[102:105]
	v_mfma_f32_16x16x32_bf16 v[106:109], v[40:43], v[30:33], v[106:109]
	s_waitcnt vmcnt(6)
	v_mfma_f32_16x16x32_bf16 v[94:97], v[48:51], v[52:55], v[94:97]
	s_waitcnt vmcnt(5)
	v_mfma_f32_16x16x32_bf16 v[98:101], v[48:51], v[56:59], v[98:101]
	s_waitcnt vmcnt(2)
	v_mfma_f32_16x16x32_bf16 v[102:105], v[82:85], v[52:55], v[102:105]
	v_mfma_f32_16x16x32_bf16 v[106:109], v[82:85], v[56:59], v[106:109]
	v_mfma_f32_16x16x32_bf16 v[94:97], v[70:73], v[60:63], v[94:97]
	s_waitcnt vmcnt(1)
	v_mfma_f32_16x16x32_bf16 v[98:101], v[70:73], v[86:89], v[98:101]
	s_waitcnt vmcnt(0)
	v_mfma_f32_16x16x32_bf16 v[102:105], v[90:93], v[60:63], v[102:105]
	v_mfma_f32_16x16x32_bf16 v[106:109], v[90:93], v[86:89], v[106:109]
	s_nop 9
	ds_write_b128 v79, v[94:97]
	ds_write_b128 v79, v[98:101] offset:2304
	ds_write_b128 v79, v[102:105] offset:64
	ds_write_b128 v79, v[106:109] offset:2368
	s_waitcnt lgkmcnt(0)
	s_barrier
	s_and_saveexec_b64 s[8:9], s[6:7]
	s_cbranch_execz .LBB0_1871
	ds_read_b128 v[60:63], v80
	ds_read_b128 v[56:59], v80 offset:16
	ds_read_b128 v[52:55], v80 offset:4608
	ds_read_b128 v[48:51], v80 offset:4624
	ds_read_b128 v[44:47], v80 offset:9216
	ds_read_b128 v[40:43], v80 offset:9232
	ds_read_b128 v[36:39], v80 offset:13824
	ds_read_b128 v[32:35], v80 offset:13840
	ds_read_b128 v[28:31], v80 offset:18432
	ds_read_b128 v[24:27], v80 offset:18448
	ds_read_b128 v[20:23], v80 offset:23040
	ds_read_b128 v[16:19], v80 offset:23056
	ds_read_b128 v[12:15], v80 offset:27648
	ds_read_b128 v[8:11], v80 offset:27664
	ds_read_b128 v[4:7], v80 offset:32256
	ds_read_b128 v[0:3], v80 offset:32272
	v_or_b32_e32 v70, s12, v78
	v_cmp_lt_i32_e32 vcc, s22, v70
	v_mov_b32_e32 v64, 0x3db504f3
	v_mov_b64_e32 v[74:75], 0x200
	v_mov_b64_e32 v[72:73], s[68:69]
	s_and_saveexec_b64 s[12:13], vcc
	s_cbranch_execz .LBB0_1870
	s_cmpk_gt_u32 s3, 0x3ff
	s_mov_b64 s[16:17], -1
	s_cbranch_scc0 .LBB0_1876
	v_add_u32_e32 v71, 0xfffffc00, v70
	s_mov_b64 s[16:17], 0

;     ...
;         for (int s0 = 0; s0 < ksteps; s0 += 4) {
;             bf16x8 a0[4], a1[4], b0[4], b1[4];
; #pragma unroll
;             for (int j = 0; j < 4; ++j) if (s0 + j < ksteps) { const int s = s0 + j;
;                 a0[j] = *(const bf16x8*)(ap + 32 * s); a1[j] = *(const bf16x8*)(ap + (size_t)16 * lda + 32 * s);
;                 b0[j] = *(const bf16x8*)(bp + 32 * s); b1[j] = *(const bf16x8*)(bp + (size_t)16 * ldb + 32 * s); }
; #pragma unroll
;             for (int j = 0; j < 4; ++j) if (s0 + j < ksteps) {
;                 acc[0][0] = __builtin_amdgcn_mfma_f32_16x16x32_bf16(b0[j], a0[j], acc[0][0], 0, 0, 0); acc[0][1] = __builtin_amdgcn_mfma_f32_16x16x32_bf16(b1[j], a0[j], acc[0][1], 0, 0, 0);
;                 acc[1][0] = __builtin_amdgcn_mfma_f32_16x16x32_bf16(b0[j], a1[j], acc[1][0], 0, 0, 0); acc[1][1] = __builtin_amdgcn_mfma_f32_16x16x32_bf16(b1[j], a1[j], acc[1][1], 0, 0, 0); } }
; #pragma unroll
;         for (int i = 0; i < 2; ++i)
; #pragma unroll
;             for (int j = 0; j < 2; ++j) *(f32x4*)(part + (wid * 32 + 16 * i + fr) * 36 + 16 * j + 4 * fq) = acc[i][j];
;         __syncthreads();
.LBB0_1902:
	s_and_b32 s8, s3, 0xffffffe0
	v_or_b32_e32 v12, s8, v6
	v_ashrrev_i32_e32 v13, 31, v12
	v_lshlrev_b64 v[12:13], 11, v[12:13]
	s_and_b32 s9, s13, 0xe0
	v_lshl_add_u64 v[48:49], v[4:5], 0, v[12:13]
	s_bitset1_b32 s9, 14
	v_or_b32_e32 v0, s9, v6
	v_lshlrev_b32_e32 v0, 11, v0
	v_lshl_add_u64 v[50:51], v[2:3], 0, v[0:1]
	v_add_co_u32_e32 v56, vcc, s15, v50
	v_addc_co_u32_e32 v57, vcc, 0, v51, vcc
	v_add_co_u32_e32 v58, vcc, s15, v48
	v_addc_co_u32_e32 v59, vcc, 0, v49, vcc
	global_load_dwordx4 v[14:17], v[48:49], off
	global_load_dwordx4 v[18:21], v[50:51], off
	global_load_dwordx4 v[22:25], v[56:57], off
	global_load_dwordx4 v[26:29], v[50:51], off offset:64
	global_load_dwordx4 v[30:33], v[48:49], off offset:64
	global_load_dwordx4 v[34:37], v[58:59], off
	global_load_dwordx4 v[38:41], v[56:57], off offset:64
	global_load_dwordx4 v[42:45], v[58:59], off offset:64
	global_load_dwordx4 v[52:55], v[48:49], off offset:128
	global_load_dwordx4 v[60:63], v[50:51], off offset:128
	global_load_dwordx4 v[64:67], v[56:57], off offset:128
	global_load_dwordx4 v[68:71], v[50:51], off offset:192
	global_load_dwordx4 v[72:75], v[48:49], off offset:192
	global_load_dwordx4 v[76:79], v[58:59], off offset:128
	global_load_dwordx4 v[80:83], v[56:57], off offset:192
	global_load_dwordx4 v[84:87], v[58:59], off offset:192
	s_waitcnt vmcnt(14)
	v_mfma_f32_16x16x32_bf16 v[88:91], v[14:17], v[18:21], 0
	s_waitcnt vmcnt(13)
	v_mfma_f32_16x16x32_bf16 v[92:95], v[14:17], v[22:25], 0
	s_waitcnt vmcnt(10)
	v_mfma_f32_16x16x32_bf16 v[96:99], v[34:37], v[18:21], 0
	v_mfma_f32_16x16x32_bf16 v[88:91], v[30:33], v[26:29], v[88:91]
	s_waitcnt vmcnt(9)
	v_mfma_f32_16x16x32_bf16 v[92:95], v[30:33], v[38:41], v[92:95]
	v_mfma_f32_16x16x32_bf16 v[100:103], v[34:37], v[22:25], 0
	s_waitcnt vmcnt(8)
	v_mfma_f32_16x16x32_bf16 v[96:99], v[42:45], v[26:29], v[96:99]
	v_mfma_f32_16x16x32_bf16 v[100:103], v[42:45], v[38:41], v[100:103]
	s_waitcnt vmcnt(6)
	v_mfma_f32_16x16x32_bf16 v[88:91], v[52:55], v[60:63], v[88:91]
	s_waitcnt vmcnt(5)
	v_mfma_f32_16x16x32_bf16 v[92:95], v[52:55], v[64:67], v[92:95]
	s_waitcnt vmcnt(2)
	v_mfma_f32_16x16x32_bf16 v[96:99], v[76:79], v[60:63], v[96:99]
	v_mfma_f32_16x16x32_bf16 v[100:103], v[76:79], v[64:67], v[100:103]
	v_mfma_f32_16x16x32_bf16 v[88:91], v[72:75], v[68:71], v[88:91]
	s_waitcnt vmcnt(1)
	v_mfma_f32_16x16x32_bf16 v[92:95], v[72:75], v[80:83], v[92:95]
	s_waitcnt vmcnt(0)
	v_mfma_f32_16x16x32_bf16 v[96:99], v[84:87], v[68:71], v[96:99]
	v_mfma_f32_16x16x32_bf16 v[100:103], v[84:87], v[80:83], v[100:103]
	s_nop 9
	ds_write_b128 v9, v[88:91]
	ds_write_b128 v9, v[92:95] offset:2304
	ds_write_b128 v9, v[96:99] offset:64
	ds_write_b128 v9, v[100:103] offset:2368
	s_waitcnt lgkmcnt(0)
	s_barrier
	s_and_saveexec_b64 s[10:11], s[6:7]
	s_cbranch_execz .LBB0_1901
; __device__ __forceinline__ float rinv_of(float ssq) { return rsqrtf(ssq * (1.0f / 1024.0f) + EPS); }
; __device__ __forceinline__ u32x4 pack8(const f32x4 a, const f32x4 b) { u32x4 w; w.x = cvt_pk_bf16(a[0], a[1]); w.y = cvt_pk_bf16(a[2], a[3]); w.z = cvt_pk_bf16(b[0], b[1]); w.w = cvt_pk_bf16(b[2], b[3]); return w; }
;     __device__ __forceinline__ float apply8(int r, int c, const f32x4 a0, const f32x4 a1) const { *(u32x4*)(O + (size_t)r * ldc + c) = pack8(a0, a1); return 0.f; }
;     __device__ __forceinline__ float apply8(int r, int c, const f32x4 a0, const f32x4 a1) const {
;         const float ri = rinv_of(ssq_in[r]); const u32x4 w = pack8(a0 * ri, a1 * ri); bf16_t* p = vT + (size_t)c * MPAD + r;
;         p[0] = (bf16_t)(w.x & 0xffffu); p[MPAD] = (bf16_t)(w.x >> 16); p[2 * (size_t)MPAD] = (bf16_t)(w.y & 0xffffu); p[3 * (size_t)MPAD] = (bf16_t)(w.y >> 16);
;         p[4 * (size_t)MPAD] = (bf16_t)(w.z & 0xffffu); p[5 * (size_t)MPAD] = (bf16_t)(w.z >> 16); p[6 * (size_t)MPAD] = (bf16_t)(w.w & 0xffffu); p[7 * (size_t)MPAD] = (bf16_t)(w.w >> 16); return 0.f; }
;     ...
;         if (tid < 128) { const int row = tid >> 2, oct = tid & 3; f32x4 v0 = (f32x4){0.f, 0.f, 0.f, 0.f}, v1 = v0;
; #pragma unroll
;             for (int w = 0; w < 8; ++w) { v0 += *(const f32x4*)(part + (w * 32 + row) * 36 + 8 * oct); v1 += *(const f32x4*)(part + (w * 32 + row) * 36 + 8 * oct + 4); }
;             float sq = E.apply8(r0 + row, c0 + 8 * oct, v0, v1);
	v_add_u32_e32 v76, s9, v7
	v_ashrrev_i32_e32 v77, 31, v76
	v_lshl_add_u64 v[12:13], v[76:77], 2, s[34:35]
	global_load_dword v0, v[12:13], off
	ds_read_b128 v[12:15], v10
	ds_read_b128 v[16:19], v10 offset:16
	ds_read_b128 v[20:23], v10 offset:4608
	ds_read_b128 v[24:27], v10 offset:4624
	ds_read_b128 v[28:31], v10 offset:9216
	ds_read_b128 v[32:35], v10 offset:9232
	ds_read_b128 v[36:39], v10 offset:13824
	ds_read_b128 v[40:43], v10 offset:13840
	ds_read_b128 v[44:47], v10 offset:18432
	ds_read_b128 v[48:51], v10 offset:18448
	ds_read_b128 v[52:55], v10 offset:23040
	ds_read_b128 v[56:59], v10 offset:23056
	ds_read_b128 v[60:63], v10 offset:27648
	ds_read_b128 v[64:67], v10 offset:27664
	ds_read_b128 v[68:71], v10 offset:32256
	ds_read_b128 v[72:75], v10 offset:32272
	v_or_b32_e32 v80, s8, v8
	v_mov_b64_e32 v[78:79], s[74:75]
	v_mad_i64_i32 v[78:79], s[8:9], v80, s17, v[78:79]
	s_waitcnt lgkmcnt(14)
	v_pk_add_f32 v[12:13], v[12:13], 0 op_sel_hi:[1,0]
	v_lshl_add_u64 v[76:77], v[76:77], 1, v[78:79]
	s_waitcnt lgkmcnt(13)
	v_pk_add_f32 v[12:13], v[12:13], v[20:21]
	v_pk_add_f32 v[14:15], v[14:15], 0 op_sel_hi:[1,0]
	v_pk_add_f32 v[18:19], v[18:19], 0 op_sel_hi:[1,0]
	v_pk_add_f32 v[16:17], v[16:17], 0 op_sel_hi:[1,0]
	v_add_co_u32_e32 v78, vcc, s15, v76
	v_pk_add_f32 v[14:15], v[14:15], v[22:23]
	s_waitcnt lgkmcnt(12)
	v_pk_add_f32 v[18:19], v[18:19], v[26:27]
	v_pk_add_f32 v[16:17], v[16:17], v[24:25]
	s_waitcnt lgkmcnt(11)
	v_pk_add_f32 v[12:13], v[12:13], v[28:29]
	v_addc_co_u32_e32 v79, vcc, 0, v77, vcc
	v_pk_add_f32 v[14:15], v[14:15], v[30:31]
	s_waitcnt lgkmcnt(10)
	v_pk_add_f32 v[18:19], v[18:19], v[34:35]
	v_pk_add_f32 v[16:17], v[16:17], v[32:33]
	s_waitcnt lgkmcnt(9)
	v_pk_add_f32 v[12:13], v[12:13], v[36:37]
	v_add_co_u32_e32 v80, vcc, s18, v76
	v_pk_add_f32 v[14:15], v[14:15], v[38:39]
	s_waitcnt lgkmcnt(8)
	v_pk_add_f32 v[18:19], v[18:19], v[42:43]
	v_pk_add_f32 v[16:17], v[16:17], v[40:41]
	s_waitcnt lgkmcnt(7)
	v_pk_add_f32 v[12:13], v[12:13], v[44:45]
	v_addc_co_u32_e32 v81, vcc, 0, v77, vcc
	v_pk_add_f32 v[14:15], v[14:15], v[46:47]
	s_waitcnt lgkmcnt(6)
	v_pk_add_f32 v[18:19], v[18:19], v[50:51]
	v_pk_add_f32 v[16:17], v[16:17], v[48:49]
	s_waitcnt lgkmcnt(5)
	v_pk_add_f32 v[12:13], v[12:13], v[52:53]
	v_add_co_u32_e32 v82, vcc, s19, v76
	v_pk_add_f32 v[14:15], v[14:15], v[54:55]
	s_waitcnt lgkmcnt(4)
	v_pk_add_f32 v[18:19], v[18:19], v[58:59]
	v_pk_add_f32 v[16:17], v[16:17], v[56:57]
	s_waitcnt lgkmcnt(3)
	v_pk_add_f32 v[12:13], v[12:13], v[60:61]
	v_addc_co_u32_e32 v83, vcc, 0, v77, vcc
	v_pk_add_f32 v[14:15], v[14:15], v[62:63]
	s_waitcnt lgkmcnt(2)
	v_pk_add_f32 v[18:19], v[18:19], v[66:67]
	v_pk_add_f32 v[16:17], v[16:17], v[64:65]
	s_waitcnt lgkmcnt(1)
	v_pk_add_f32 v[12:13], v[12:13], v[68:69]
	v_add_co_u32_e32 v20, vcc, 0x20000, v76
	v_pk_add_f32 v[14:15], v[14:15], v[70:71]
	s_waitcnt lgkmcnt(0)
	v_pk_add_f32 v[18:19], v[18:19], v[74:75]
	v_pk_add_f32 v[16:17], v[16:17], v[72:73]
	s_waitcnt vmcnt(0)
	v_fmamk_f32 v0, v0, 0x3a800000, v11
	v_mul_f32_e32 v21, 0x4b800000, v0
	v_cmp_gt_f32_e64 s[8:9], s16, v0
	s_nop 1
	v_cndmask_b32_e64 v0, v0, v21, s[8:9]
	v_rsq_f32_e32 v0, v0
	s_nop 0
	v_mul_f32_e32 v21, 0x45800000, v0
	v_cndmask_b32_e64 v0, v0, v21, s[8:9]
	v_pk_mul_f32 v[12:13], v[12:13], v[0:1] op_sel_hi:[1,0]
	v_pk_mul_f32 v[14:15], v[14:15], v[0:1] op_sel_hi:[1,0]
	v_pk_mul_f32 v[18:19], v[18:19], v[0:1] op_sel_hi:[1,0]
	v_pk_mul_f32 v[16:17], v[16:17], v[0:1] op_sel_hi:[1,0]
	v_cvt_pk_bf16_f32 v0, v12, v13
	v_cvt_pk_bf16_f32 v12, v14, v15
	v_addc_co_u32_e32 v21, vcc, 0, v77, vcc
	v_cvt_pk_bf16_f32 v14, v16, v17
	v_cvt_pk_bf16_f32 v15, v18, v19
	global_store_short v[76:77], v0, off
	global_store_short_d16_hi v[78:79], v0, off offset:640
	global_store_short v[80:81], v12, off offset:1280
	global_store_short_d16_hi v[82:83], v12, off offset:1920
	v_add_co_u32_e32 v12, vcc, 0x28000, v76
	global_store_short v[20:21], v14, off offset:2560
	s_nop 0
	v_addc_co_u32_e32 v13, vcc, 0, v77, vcc
	global_store_short_d16_hi v[12:13], v14, off offset:3200
	v_add_co_u32_e32 v12, vcc, 0x30000, v76
	s_nop 1
	v_addc_co_u32_e32 v13, vcc, 0, v77, vcc
	global_store_short v[12:13], v15, off offset:3840
	v_add_co_u32_e32 v12, vcc, 0x39000, v76
	s_nop 1
	v_addc_co_u32_e32 v13, vcc, 0, v77, vcc
	global_store_short_d16_hi v[12:13], v15, off offset:384
	s_branch .LBB0_1901

;     ...
;         for (int s0 = 0; s0 < ksteps; s0 += 4) {
;             bf16x8 a0[4], a1[4], b0[4], b1[4];
; #pragma unroll
;             for (int j = 0; j < 4; ++j) if (s0 + j < ksteps) { const int s = s0 + j;
;                 a0[j] = *(const bf16x8*)(ap + 32 * s); a1[j] = *(const bf16x8*)(ap + (size_t)16 * lda + 32 * s);
;                 b0[j] = *(const bf16x8*)(bp + 32 * s); b1[j] = *(const bf16x8*)(bp + (size_t)16 * ldb + 32 * s); }
; #pragma unroll
;             for (int j = 0; j < 4; ++j) if (s0 + j < ksteps) {
;                 acc[0][0] = __builtin_amdgcn_mfma_f32_16x16x32_bf16(b0[j], a0[j], acc[0][0], 0, 0, 0); acc[0][1] = __builtin_amdgcn_mfma_f32_16x16x32_bf16(b1[j], a0[j], acc[0][1], 0, 0, 0);
;                 acc[1][0] = __builtin_amdgcn_mfma_f32_16x16x32_bf16(b0[j], a1[j], acc[1][0], 0, 0, 0); acc[1][1] = __builtin_amdgcn_mfma_f32_16x16x32_bf16(b1[j], a1[j], acc[1][1], 0, 0, 0); } }
; #pragma unroll
;         for (int i = 0; i < 2; ++i)
; #pragma unroll
;             for (int j = 0; j < 2; ++j) *(f32x4*)(part + (wid * 32 + 16 * i + fr) * 36 + 16 * j + 4 * fq) = acc[i][j];
;         __syncthreads();
.LBB0_2319:
	s_and_b32 s19, s3, 0xffffffe0
	v_or_b32_e32 v14, s19, v10
	v_ashrrev_i32_e32 v15, 31, v14
	v_lshlrev_b64 v[14:15], 11, v[14:15]
	s_and_b32 s10, s15, 0xe0
	v_lshl_add_u64 v[50:51], v[4:5], 0, v[14:15]
	s_bitset1_b32 s10, 14
	v_or_b32_e32 v0, s10, v10
	v_lshlrev_b32_e32 v0, 11, v0
	v_lshl_add_u64 v[52:53], v[2:3], 0, v[0:1]
	v_add_co_u32_e32 v58, vcc, s17, v52
	v_addc_co_u32_e32 v59, vcc, 0, v53, vcc
	v_add_co_u32_e32 v60, vcc, s17, v50
	v_addc_co_u32_e32 v61, vcc, 0, v51, vcc
	global_load_dwordx4 v[16:19], v[50:51], off
	global_load_dwordx4 v[20:23], v[52:53], off
	global_load_dwordx4 v[24:27], v[58:59], off
	global_load_dwordx4 v[28:31], v[52:53], off offset:64
	global_load_dwordx4 v[32:35], v[50:51], off offset:64
	global_load_dwordx4 v[36:39], v[60:61], off
	global_load_dwordx4 v[40:43], v[58:59], off offset:64
	global_load_dwordx4 v[44:47], v[60:61], off offset:64
	global_load_dwordx4 v[54:57], v[50:51], off offset:128
	global_load_dwordx4 v[62:65], v[52:53], off offset:128
	global_load_dwordx4 v[66:69], v[58:59], off offset:128
	global_load_dwordx4 v[70:73], v[52:53], off offset:192
	global_load_dwordx4 v[74:77], v[50:51], off offset:192
	global_load_dwordx4 v[78:81], v[60:61], off offset:128
	global_load_dwordx4 v[82:85], v[58:59], off offset:192
	global_load_dwordx4 v[86:89], v[60:61], off offset:192
	s_waitcnt vmcnt(14)
	v_mfma_f32_16x16x32_bf16 v[90:93], v[16:19], v[20:23], 0
	s_waitcnt vmcnt(13)
	v_mfma_f32_16x16x32_bf16 v[94:97], v[16:19], v[24:27], 0
	s_waitcnt vmcnt(10)
	v_mfma_f32_16x16x32_bf16 v[98:101], v[36:39], v[20:23], 0
	v_mfma_f32_16x16x32_bf16 v[90:93], v[32:35], v[28:31], v[90:93]
	s_waitcnt vmcnt(9)
	v_mfma_f32_16x16x32_bf16 v[94:97], v[32:35], v[40:43], v[94:97]
	v_mfma_f32_16x16x32_bf16 v[102:105], v[36:39], v[24:27], 0
	s_waitcnt vmcnt(8)
	v_mfma_f32_16x16x32_bf16 v[98:101], v[44:47], v[28:31], v[98:101]
	v_mfma_f32_16x16x32_bf16 v[102:105], v[44:47], v[40:43], v[102:105]
	s_waitcnt vmcnt(6)
	v_mfma_f32_16x16x32_bf16 v[90:93], v[54:57], v[62:65], v[90:93]
	s_waitcnt vmcnt(5)
	v_mfma_f32_16x16x32_bf16 v[94:97], v[54:57], v[66:69], v[94:97]
	s_waitcnt vmcnt(2)
	v_mfma_f32_16x16x32_bf16 v[98:101], v[78:81], v[62:65], v[98:101]
	v_mfma_f32_16x16x32_bf16 v[102:105], v[78:81], v[66:69], v[102:105]
	v_mfma_f32_16x16x32_bf16 v[90:93], v[74:77], v[70:73], v[90:93]
	s_waitcnt vmcnt(1)
	v_mfma_f32_16x16x32_bf16 v[94:97], v[74:77], v[82:85], v[94:97]
	s_waitcnt vmcnt(0)
	v_mfma_f32_16x16x32_bf16 v[98:101], v[86:89], v[70:73], v[98:101]
	v_mfma_f32_16x16x32_bf16 v[102:105], v[86:89], v[82:85], v[102:105]
	s_nop 9
	ds_write_b128 v7, v[90:93]
	ds_write_b128 v7, v[94:97] offset:2304
	ds_write_b128 v7, v[98:101] offset:64
	ds_write_b128 v7, v[102:105] offset:2368
	s_waitcnt lgkmcnt(0)
	s_barrier
	s_and_saveexec_b64 s[12:13], s[6:7]
	s_cbranch_execz .LBB0_2318
; __device__ __forceinline__ u32x4 pack8(const f32x4 a, const f32x4 b) { u32x4 w; w.x = cvt_pk_bf16(a[0], a[1]); w.y = cvt_pk_bf16(a[2], a[3]); w.z = cvt_pk_bf16(b[0], b[1]); w.w = cvt_pk_bf16(b[2], b[3]); return w; }
; __device__ __forceinline__ float sq8(const f32x4 a, const f32x4 b) { return (a[0] * a[0] + a[1] * a[1]) + (a[2] * a[2] + a[3] * a[3]) + (b[0] * b[0] + b[1] * b[1]) + (b[2] * b[2] + b[3] * b[3]); }
;     __device__ __forceinline__ float apply8(int r, int c, const f32x4 a0, const f32x4 a1) const { *(u32x4*)(O + (size_t)r * ldc + c) = pack8(a0, a1); return 0.f; }
;     __device__ __forceinline__ float apply8(int r, int c, const f32x4 a0, const f32x4 a1) const {
;         float* hp = h + (size_t)r * D + c; const f32x4 v0 = *(const f32x4*)hp + a0 * mul, v1 = *(const f32x4*)(hp + 4) + a1 * mul;
;         *(f32x4*)hp = v0; *(f32x4*)(hp + 4) = v1; *(u32x4*)(hb + (size_t)r * D + c) = pack8(v0, v1); return sq8(v0, v1); }
;     ...
;         if (tid < 128) { const int row = tid >> 2, oct = tid & 3; f32x4 v0 = (f32x4){0.f, 0.f, 0.f, 0.f}, v1 = v0;
; #pragma unroll
;             for (int w = 0; w < 8; ++w) { v0 += *(const f32x4*)(part + (w * 32 + row) * 36 + 8 * oct); v1 += *(const f32x4*)(part + (w * 32 + row) * 36 + 8 * oct + 4); }
;             float sq = E.apply8(r0 + row, c0 + 8 * oct, v0, v1);
;             if (Epi::HAS_SSQ) { sq += __shfl_xor(sq, 1); sq += __shfl_xor(sq, 2); if (oct == 0) atomicAdd(E.ssq + r0 + row, sq); } }
	v_add_u32_e32 v86, s10, v6
	v_ashrrev_i32_e32 v87, 31, v86
	v_or_b32_e32 v88, s19, v11
	v_lshlrev_b64 v[14:15], 12, v[86:87]
	v_lshl_add_u64 v[14:15], s[52:53], 0, v[14:15]
	v_ashrrev_i32_e32 v89, 31, v88
	v_lshl_add_u64 v[90:91], v[88:89], 2, v[14:15]
	global_load_dwordx4 v[14:17], v[90:91], off
	global_load_dwordx4 v[18:21], v[90:91], off offset:16
	ds_read_b128 v[22:25], v12
	ds_read_b128 v[26:29], v12 offset:16
	ds_read_b128 v[30:33], v12 offset:4608
	ds_read_b128 v[34:37], v12 offset:4624
	ds_read_b128 v[38:41], v12 offset:9216
	ds_read_b128 v[42:45], v12 offset:9232
	ds_read_b128 v[46:49], v12 offset:13824
	ds_read_b128 v[50:53], v12 offset:13840
	ds_read_b128 v[54:57], v12 offset:18432
	ds_read_b128 v[58:61], v12 offset:18448
	ds_read_b128 v[62:65], v12 offset:23040
	ds_read_b128 v[66:69], v12 offset:23056
	ds_read_b128 v[70:73], v12 offset:27648
	ds_read_b128 v[74:77], v12 offset:27664
	ds_read_b128 v[78:81], v12 offset:32256
	ds_read_b128 v[82:85], v12 offset:32272
	s_waitcnt lgkmcnt(14)
	v_pk_add_f32 v[24:25], v[24:25], 0 op_sel_hi:[1,0]
	v_pk_add_f32 v[22:23], v[22:23], 0 op_sel_hi:[1,0]
	v_pk_add_f32 v[26:27], v[26:27], 0 op_sel_hi:[1,0]
	s_waitcnt lgkmcnt(13)
	v_pk_add_f32 v[24:25], v[24:25], v[32:33]
	v_pk_add_f32 v[22:23], v[22:23], v[30:31]
	v_pk_add_f32 v[28:29], v[28:29], 0 op_sel_hi:[1,0]
	s_waitcnt lgkmcnt(12)
	v_pk_add_f32 v[26:27], v[26:27], v[34:35]
	s_waitcnt lgkmcnt(11)
	v_pk_add_f32 v[24:25], v[24:25], v[40:41]
	v_pk_add_f32 v[22:23], v[22:23], v[38:39]
	v_pk_add_f32 v[28:29], v[28:29], v[36:37]
	s_waitcnt lgkmcnt(10)
	v_pk_add_f32 v[26:27], v[26:27], v[42:43]
	s_waitcnt lgkmcnt(9)
	v_pk_add_f32 v[24:25], v[24:25], v[48:49]
	v_pk_add_f32 v[22:23], v[22:23], v[46:47]
	v_pk_add_f32 v[28:29], v[28:29], v[44:45]
	s_waitcnt lgkmcnt(8)
	v_pk_add_f32 v[26:27], v[26:27], v[50:51]
	s_waitcnt lgkmcnt(7)
	v_pk_add_f32 v[24:25], v[24:25], v[56:57]
	v_pk_add_f32 v[22:23], v[22:23], v[54:55]
	v_pk_add_f32 v[28:29], v[28:29], v[52:53]
	s_waitcnt lgkmcnt(6)
	v_pk_add_f32 v[26:27], v[26:27], v[58:59]
	s_waitcnt lgkmcnt(5)
	v_pk_add_f32 v[24:25], v[24:25], v[64:65]
	v_pk_add_f32 v[22:23], v[22:23], v[62:63]
	v_pk_add_f32 v[28:29], v[28:29], v[60:61]
	s_waitcnt lgkmcnt(4)
	v_pk_add_f32 v[26:27], v[26:27], v[66:67]
	s_waitcnt lgkmcnt(3)
	v_pk_add_f32 v[24:25], v[24:25], v[72:73]
	v_pk_add_f32 v[22:23], v[22:23], v[70:71]
	v_pk_add_f32 v[28:29], v[28:29], v[68:69]
	s_waitcnt lgkmcnt(2)
	v_pk_add_f32 v[26:27], v[26:27], v[74:75]
	s_waitcnt lgkmcnt(1)
	v_pk_add_f32 v[24:25], v[24:25], v[80:81]
	v_pk_add_f32 v[22:23], v[22:23], v[78:79]
	v_pk_add_f32 v[28:29], v[28:29], v[76:77]
	s_waitcnt lgkmcnt(0)
	v_pk_add_f32 v[26:27], v[26:27], v[82:83]
	v_and_b32_e32 v92, 64, v13
	v_pk_add_f32 v[28:29], v[28:29], v[84:85]
	v_xor_b32_e32 v0, 1, v13
	v_add_u32_e32 v92, 64, v92
	v_cmp_lt_i32_e32 vcc, v0, v92
	v_xor_b32_e32 v93, 2, v13
	s_waitcnt vmcnt(1)
	v_pk_add_f32 v[16:17], v[24:25], v[16:17]
	v_pk_add_f32 v[14:15], v[22:23], v[14:15]
	s_waitcnt vmcnt(0)
	v_pk_add_f32 v[18:19], v[26:27], v[18:19]
	v_mul_f32_e32 v22, v15, v15
	v_mul_f32_e32 v23, v17, v17
	v_pk_add_f32 v[20:21], v[28:29], v[20:21]
	v_mul_f32_e32 v24, v19, v19
	v_fmac_f32_e32 v22, v14, v14
	v_fmac_f32_e32 v23, v16, v16
	v_mul_f32_e32 v25, v21, v21
	v_fmac_f32_e32 v24, v18, v18
	v_add_f32_e32 v22, v22, v23
	v_cndmask_b32_e32 v0, v13, v0, vcc
	v_fmac_f32_e32 v25, v20, v20
	v_add_f32_e32 v22, v24, v22
	v_lshlrev_b32_e32 v0, 2, v0
	v_add_f32_e32 v26, v25, v22
	ds_bpermute_b32 v0, v0, v26
	v_cmp_lt_i32_e32 vcc, v93, v92
	global_store_dwordx4 v[90:91], v[14:17], off
	global_store_dwordx4 v[90:91], v[18:21], off offset:16
	v_cndmask_b32_e32 v92, v13, v93, vcc
	v_cvt_pk_bf16_f32 v22, v14, v15
	s_waitcnt lgkmcnt(0)
	v_add_f32_e32 v0, v26, v0
	v_lshlrev_b32_e32 v14, 2, v92
	ds_bpermute_b32 v14, v14, v0
	v_cvt_pk_bf16_f32 v23, v16, v17
	v_lshlrev_b64 v[16:17], 11, v[86:87]
	v_lshl_add_u64 v[16:17], s[68:69], 0, v[16:17]
	v_lshl_add_u64 v[16:17], v[88:89], 1, v[16:17]
	v_cvt_pk_bf16_f32 v24, v18, v19
	v_cvt_pk_bf16_f32 v25, v20, v21
	global_store_dwordx4 v[16:17], v[22:25], off
	s_and_b64 exec, exec, s[8:9]
	s_cbranch_execz .LBB0_2318
	s_lshl_b32 s10, s10, 2
	v_lshl_add_u64 v[16:17], v[8:9], 0, s[10:11]
	s_waitcnt lgkmcnt(0)
	v_add_f32_e32 v0, v0, v14
	global_atomic_add_f32 v[16:17], v0, off
	s_branch .LBB0_2318

;     ...
;         for (int s0 = 0; s0 < ksteps; s0 += 4) {
;             bf16x8 a0[4], a1[4], b0[4], b1[4];
; #pragma unroll
;             for (int j = 0; j < 4; ++j) if (s0 + j < ksteps) { const int s = s0 + j;
;                 a0[j] = *(const bf16x8*)(ap + 32 * s); a1[j] = *(const bf16x8*)(ap + (size_t)16 * lda + 32 * s);
;                 b0[j] = *(const bf16x8*)(bp + 32 * s); b1[j] = *(const bf16x8*)(bp + (size_t)16 * ldb + 32 * s); }
; #pragma unroll
;             for (int j = 0; j < 4; ++j) if (s0 + j < ksteps) {
;                 acc[0][0] = __builtin_amdgcn_mfma_f32_16x16x32_bf16(b0[j], a0[j], acc[0][0], 0, 0, 0); acc[0][1] = __builtin_amdgcn_mfma_f32_16x16x32_bf16(b1[j], a0[j], acc[0][1], 0, 0, 0);
;                 acc[1][0] = __builtin_amdgcn_mfma_f32_16x16x32_bf16(b0[j], a1[j], acc[1][0], 0, 0, 0); acc[1][1] = __builtin_amdgcn_mfma_f32_16x16x32_bf16(b1[j], a1[j], acc[1][1], 0, 0, 0); } }
; #pragma unroll
;         for (int i = 0; i < 2; ++i)
; #pragma unroll
;             for (int j = 0; j < 2; ++j) *(f32x4*)(part + (wid * 32 + 16 * i + fr) * 36 + 16 * j + 4 * fq) = acc[i][j];
;         __syncthreads();
.LBB0_2543:
	s_and_b32 s19, s3, 0xffffffe0
	s_and_b32 s10, s15, 0xe0
	v_or_b32_e32 v14, s19, v10
	s_bitset1_b32 s10, 14
	v_mad_i64_i32 v[70:71], s[12:13], v14, s17, v[4:5]
	v_or_b32_e32 v0, s10, v10
	v_mul_u32_u24_e32 v0, 0xb00, v0
	v_lshlrev_b32_e32 v0, 1, v0
	v_lshl_add_u64 v[72:73], v[2:3], 0, v[0:1]
	v_add_co_u32_e32 v74, vcc, 0x16000, v72
	v_addc_co_u32_e32 v75, vcc, 0, v73, vcc
	v_add_co_u32_e32 v76, vcc, 0x16000, v70
	v_addc_co_u32_e32 v77, vcc, 0, v71, vcc
	global_load_dwordx4 v[16:19], v[70:71], off
	global_load_dwordx4 v[20:23], v[72:73], off
	global_load_dwordx4 v[24:27], v[70:71], off offset:64
	global_load_dwordx4 v[28:31], v[74:75], off
	global_load_dwordx4 v[32:35], v[72:73], off offset:64
	global_load_dwordx4 v[36:39], v[72:73], off offset:640
	global_load_dwordx4 v[40:43], v[74:75], off offset:64
	global_load_dwordx4 v[44:47], v[70:71], off offset:128
	global_load_dwordx4 v[48:51], v[76:77], off
	global_load_dwordx4 v[52:55], v[74:75], off offset:640
	global_load_dwordx4 v[56:59], v[72:73], off offset:128
	global_load_dwordx4 v[60:63], v[72:73], off offset:192
	global_load_dwordx4 v[64:67], v[74:75], off offset:128
	global_load_dwordx4 v[78:81], v[74:75], off offset:192
	global_load_dwordx4 v[82:85], v[76:77], off offset:64
	global_load_dwordx4 v[86:89], v[76:77], off offset:128
	global_load_dwordx4 v[90:93], v[70:71], off offset:192
	global_load_dwordx4 v[94:97], v[70:71], off offset:256
	global_load_dwordx4 v[98:101], v[72:73], off offset:256
	global_load_dwordx4 v[102:105], v[72:73], off offset:320
	global_load_dwordx4 v[106:109], v[74:75], off offset:256
	global_load_dwordx4 v[110:113], v[74:75], off offset:320
	global_load_dwordx4 v[114:117], v[76:77], off offset:192
	global_load_dwordx4 v[118:121], v[76:77], off offset:256
	global_load_dwordx4 v[122:125], v[70:71], off offset:320
	global_load_dwordx4 v[126:129], v[70:71], off offset:384
	global_load_dwordx4 v[130:133], v[72:73], off offset:384
	global_load_dwordx4 v[134:137], v[72:73], off offset:448
	global_load_dwordx4 v[138:141], v[74:75], off offset:384
	global_load_dwordx4 v[142:145], v[74:75], off offset:448
	global_load_dwordx4 v[146:149], v[76:77], off offset:320
	global_load_dwordx4 v[150:153], v[76:77], off offset:384
	global_load_dwordx4 v[154:157], v[70:71], off offset:448
	global_load_dwordx4 v[158:161], v[70:71], off offset:512
	global_load_dwordx4 v[162:165], v[76:77], off offset:448
	global_load_dwordx4 v[166:169], v[76:77], off offset:512
	global_load_dwordx4 v[170:173], v[72:73], off offset:512
	global_load_dwordx4 v[174:177], v[72:73], off offset:576
	global_load_dwordx4 v[178:181], v[74:75], off offset:512
	global_load_dwordx4 v[182:185], v[70:71], off offset:576
	global_load_dwordx4 v[186:189], v[74:75], off offset:576
	global_load_dwordx4 v[190:193], v[76:77], off offset:576
	global_load_dwordx4 v[194:197], v[70:71], off offset:640
	global_load_dwordx4 v[198:201], v[76:77], off offset:640
	s_waitcnt vmcnt(42)
	v_mfma_f32_16x16x32_bf16 v[202:205], v[16:19], v[20:23], 0
	s_waitcnt vmcnt(40)
	v_mfma_f32_16x16x32_bf16 v[206:209], v[16:19], v[28:31], 0
	s_waitcnt vmcnt(39)
	v_mfma_f32_16x16x32_bf16 v[202:205], v[24:27], v[32:35], v[202:205]
	s_waitcnt vmcnt(37)
	v_mfma_f32_16x16x32_bf16 v[206:209], v[24:27], v[40:43], v[206:209]
	s_waitcnt vmcnt(35)
	v_mfma_f32_16x16x32_bf16 v[212:215], v[48:51], v[20:23], 0
	v_mfma_f32_16x16x32_bf16 v[216:219], v[48:51], v[28:31], 0
	s_waitcnt vmcnt(33)
	v_mfma_f32_16x16x32_bf16 v[202:205], v[44:47], v[56:59], v[202:205]
	s_waitcnt vmcnt(31)
	v_mfma_f32_16x16x32_bf16 v[206:209], v[44:47], v[64:67], v[206:209]
	s_waitcnt vmcnt(29)
	v_mfma_f32_16x16x32_bf16 v[212:215], v[82:85], v[32:35], v[212:215]
	v_mfma_f32_16x16x32_bf16 v[216:219], v[82:85], v[40:43], v[216:219]
	s_waitcnt vmcnt(28)
	v_mfma_f32_16x16x32_bf16 v[212:215], v[86:89], v[56:59], v[212:215]
	v_mfma_f32_16x16x32_bf16 v[216:219], v[86:89], v[64:67], v[216:219]
	s_waitcnt vmcnt(27)
	v_mfma_f32_16x16x32_bf16 v[202:205], v[90:93], v[60:63], v[202:205]
	v_mfma_f32_16x16x32_bf16 v[206:209], v[90:93], v[78:81], v[206:209]
	s_waitcnt vmcnt(25)
	v_mfma_f32_16x16x32_bf16 v[202:205], v[94:97], v[98:101], v[202:205]
	s_waitcnt vmcnt(23)
	v_mfma_f32_16x16x32_bf16 v[206:209], v[94:97], v[106:109], v[206:209]
	s_waitcnt vmcnt(21)
	v_mfma_f32_16x16x32_bf16 v[212:215], v[114:117], v[60:63], v[212:215]
	v_mfma_f32_16x16x32_bf16 v[216:219], v[114:117], v[78:81], v[216:219]
	s_waitcnt vmcnt(20)
	v_mfma_f32_16x16x32_bf16 v[212:215], v[118:121], v[98:101], v[212:215]
	v_mfma_f32_16x16x32_bf16 v[216:219], v[118:121], v[106:109], v[216:219]
	s_waitcnt vmcnt(19)
	v_mfma_f32_16x16x32_bf16 v[202:205], v[122:125], v[102:105], v[202:205]
	v_mfma_f32_16x16x32_bf16 v[206:209], v[122:125], v[110:113], v[206:209]
	s_waitcnt vmcnt(17)
	v_mfma_f32_16x16x32_bf16 v[202:205], v[126:129], v[130:133], v[202:205]
	s_waitcnt vmcnt(15)
	v_mfma_f32_16x16x32_bf16 v[206:209], v[126:129], v[138:141], v[206:209]
	s_waitcnt vmcnt(13)
	v_mfma_f32_16x16x32_bf16 v[212:215], v[146:149], v[102:105], v[212:215]
	v_mfma_f32_16x16x32_bf16 v[216:219], v[146:149], v[110:113], v[216:219]
	s_waitcnt vmcnt(12)
	v_mfma_f32_16x16x32_bf16 v[212:215], v[150:153], v[130:133], v[212:215]
	v_mfma_f32_16x16x32_bf16 v[216:219], v[150:153], v[138:141], v[216:219]
	s_waitcnt vmcnt(11)
	v_mfma_f32_16x16x32_bf16 v[202:205], v[154:157], v[134:137], v[202:205]
	s_waitcnt vmcnt(9)
	v_mfma_f32_16x16x32_bf16 v[212:215], v[162:165], v[134:137], v[212:215]
	v_mfma_f32_16x16x32_bf16 v[206:209], v[154:157], v[142:145], v[206:209]
	v_mfma_f32_16x16x32_bf16 v[216:219], v[162:165], v[142:145], v[216:219]
	s_waitcnt vmcnt(7)
	v_mfma_f32_16x16x32_bf16 v[202:205], v[158:161], v[170:173], v[202:205]
	v_mfma_f32_16x16x32_bf16 v[212:215], v[166:169], v[170:173], v[212:215]
	s_waitcnt vmcnt(5)
	v_mfma_f32_16x16x32_bf16 v[206:209], v[158:161], v[178:181], v[206:209]
	v_mfma_f32_16x16x32_bf16 v[216:219], v[166:169], v[178:181], v[216:219]
	s_waitcnt vmcnt(4)
	v_mfma_f32_16x16x32_bf16 v[202:205], v[182:185], v[174:177], v[202:205]
	s_waitcnt vmcnt(2)
	v_mfma_f32_16x16x32_bf16 v[212:215], v[190:193], v[174:177], v[212:215]
	v_mfma_f32_16x16x32_bf16 v[206:209], v[182:185], v[186:189], v[206:209]
	v_mfma_f32_16x16x32_bf16 v[216:219], v[190:193], v[186:189], v[216:219]
	s_waitcnt vmcnt(1)
	v_mfma_f32_16x16x32_bf16 v[202:205], v[194:197], v[36:39], v[202:205]
	s_waitcnt vmcnt(0)
	v_mfma_f32_16x16x32_bf16 v[212:215], v[198:201], v[36:39], v[212:215]
	v_mfma_f32_16x16x32_bf16 v[206:209], v[194:197], v[52:55], v[206:209]
	v_mfma_f32_16x16x32_bf16 v[216:219], v[198:201], v[52:55], v[216:219]
	s_nop 9
	ds_write_b128 v7, v[202:205]
	ds_write_b128 v7, v[212:215] offset:64
	ds_write_b128 v7, v[206:209] offset:2304
	ds_write_b128 v7, v[216:219] offset:2368
	s_waitcnt lgkmcnt(0)
	s_barrier
; __device__ __forceinline__ u32x4 pack8(const f32x4 a, const f32x4 b) { u32x4 w; w.x = cvt_pk_bf16(a[0], a[1]); w.y = cvt_pk_bf16(a[2], a[3]); w.z = cvt_pk_bf16(b[0], b[1]); w.w = cvt_pk_bf16(b[2], b[3]); return w; }
; __device__ __forceinline__ float sq8(const f32x4 a, const f32x4 b) { return (a[0] * a[0] + a[1] * a[1]) + (a[2] * a[2] + a[3] * a[3]) + (b[0] * b[0] + b[1] * b[1]) + (b[2] * b[2] + b[3] * b[3]); }
;     __device__ __forceinline__ float apply8(int r, int c, const f32x4 a0, const f32x4 a1) const { *(u32x4*)(O + (size_t)r * ldc + c) = pack8(a0, a1); return 0.f; }
;     __device__ __forceinline__ float apply8(int r, int c, const f32x4 a0, const f32x4 a1) const {
;         float* hp = h + (size_t)r * D + c; const f32x4 v0 = *(const f32x4*)hp + a0 * mul, v1 = *(const f32x4*)(hp + 4) + a1 * mul;
;         *(f32x4*)hp = v0; *(f32x4*)(hp + 4) = v1; *(u32x4*)(hb + (size_t)r * D + c) = pack8(v0, v1); return sq8(v0, v1); }
;     ...
;         if (tid < 128) { const int row = tid >> 2, oct = tid & 3; f32x4 v0 = (f32x4){0.f, 0.f, 0.f, 0.f}, v1 = v0;
; #pragma unroll
;             for (int w = 0; w < 8; ++w) { v0 += *(const f32x4*)(part + (w * 32 + row) * 36 + 8 * oct); v1 += *(const f32x4*)(part + (w * 32 + row) * 36 + 8 * oct + 4); }
;             float sq = E.apply8(r0 + row, c0 + 8 * oct, v0, v1);
;             if (Epi::HAS_SSQ) { sq += __shfl_xor(sq, 1); sq += __shfl_xor(sq, 2); if (oct == 0) atomicAdd(E.ssq + r0 + row, sq); } }
	s_and_saveexec_b64 s[12:13], s[6:7]
	s_cbranch_execz .LBB0_2542
	v_add_u32_e32 v86, s10, v6
	v_ashrrev_i32_e32 v87, 31, v86
	v_or_b32_e32 v88, s19, v11
	v_lshlrev_b64 v[14:15], 12, v[86:87]
	v_lshl_add_u64 v[14:15], s[52:53], 0, v[14:15]
	v_ashrrev_i32_e32 v89, 31, v88
	v_lshl_add_u64 v[90:91], v[88:89], 2, v[14:15]
	global_load_dwordx4 v[14:17], v[90:91], off
	global_load_dwordx4 v[18:21], v[90:91], off offset:16
	ds_read_b128 v[22:25], v12
	ds_read_b128 v[26:29], v12 offset:16
	ds_read_b128 v[30:33], v12 offset:4608
	ds_read_b128 v[34:37], v12 offset:4624
	ds_read_b128 v[38:41], v12 offset:9216
	ds_read_b128 v[42:45], v12 offset:9232
	ds_read_b128 v[46:49], v12 offset:13824
	ds_read_b128 v[50:53], v12 offset:13840
	ds_read_b128 v[54:57], v12 offset:18432
	ds_read_b128 v[58:61], v12 offset:18448
	ds_read_b128 v[62:65], v12 offset:23040
	ds_read_b128 v[66:69], v12 offset:23056
	ds_read_b128 v[70:73], v12 offset:27648
	ds_read_b128 v[74:77], v12 offset:27664
	ds_read_b128 v[78:81], v12 offset:32256
	ds_read_b128 v[82:85], v12 offset:32272
	s_waitcnt lgkmcnt(14)
	v_pk_add_f32 v[24:25], v[24:25], 0 op_sel_hi:[1,0]
	v_pk_add_f32 v[22:23], v[22:23], 0 op_sel_hi:[1,0]
	v_pk_add_f32 v[26:27], v[26:27], 0 op_sel_hi:[1,0]
	s_waitcnt lgkmcnt(13)
	v_pk_add_f32 v[24:25], v[24:25], v[32:33]
	v_pk_add_f32 v[22:23], v[22:23], v[30:31]
	v_pk_add_f32 v[28:29], v[28:29], 0 op_sel_hi:[1,0]
	s_waitcnt lgkmcnt(12)
	v_pk_add_f32 v[26:27], v[26:27], v[34:35]
	s_waitcnt lgkmcnt(11)
	v_pk_add_f32 v[24:25], v[24:25], v[40:41]
	v_pk_add_f32 v[22:23], v[22:23], v[38:39]
	v_pk_add_f32 v[28:29], v[28:29], v[36:37]
	s_waitcnt lgkmcnt(10)
	v_pk_add_f32 v[26:27], v[26:27], v[42:43]
	s_waitcnt lgkmcnt(9)
	v_pk_add_f32 v[24:25], v[24:25], v[48:49]
	v_pk_add_f32 v[22:23], v[22:23], v[46:47]
	v_pk_add_f32 v[28:29], v[28:29], v[44:45]
	s_waitcnt lgkmcnt(8)
	v_pk_add_f32 v[26:27], v[26:27], v[50:51]
	s_waitcnt lgkmcnt(7)
	v_pk_add_f32 v[24:25], v[24:25], v[56:57]
	v_pk_add_f32 v[22:23], v[22:23], v[54:55]
	v_pk_add_f32 v[28:29], v[28:29], v[52:53]
	s_waitcnt lgkmcnt(6)
	v_pk_add_f32 v[26:27], v[26:27], v[58:59]
	s_waitcnt lgkmcnt(5)
	v_pk_add_f32 v[24:25], v[24:25], v[64:65]
	v_pk_add_f32 v[22:23], v[22:23], v[62:63]
	v_pk_add_f32 v[28:29], v[28:29], v[60:61]
	s_waitcnt lgkmcnt(4)
	v_pk_add_f32 v[26:27], v[26:27], v[66:67]
	s_waitcnt lgkmcnt(3)
	v_pk_add_f32 v[24:25], v[24:25], v[72:73]
	v_pk_add_f32 v[22:23], v[22:23], v[70:71]
	v_pk_add_f32 v[28:29], v[28:29], v[68:69]
	s_waitcnt lgkmcnt(2)
	v_pk_add_f32 v[26:27], v[26:27], v[74:75]
	s_waitcnt lgkmcnt(1)
	v_pk_add_f32 v[24:25], v[24:25], v[80:81]
	v_pk_add_f32 v[22:23], v[22:23], v[78:79]
	v_pk_add_f32 v[28:29], v[28:29], v[76:77]
	s_waitcnt lgkmcnt(0)
	v_pk_add_f32 v[26:27], v[26:27], v[82:83]
	v_and_b32_e32 v92, 64, v13
	v_pk_add_f32 v[28:29], v[28:29], v[84:85]
	v_xor_b32_e32 v0, 1, v13
	v_add_u32_e32 v92, 64, v92
	v_cmp_lt_i32_e32 vcc, v0, v92
	v_xor_b32_e32 v93, 2, v13
	s_waitcnt vmcnt(1)
	v_pk_add_f32 v[16:17], v[24:25], v[16:17]
	v_pk_add_f32 v[14:15], v[22:23], v[14:15]
	s_waitcnt vmcnt(0)
	v_pk_add_f32 v[18:19], v[26:27], v[18:19]
	v_mul_f32_e32 v22, v15, v15
	v_mul_f32_e32 v23, v17, v17
	v_pk_add_f32 v[20:21], v[28:29], v[20:21]
	v_mul_f32_e32 v24, v19, v19
	v_fmac_f32_e32 v22, v14, v14
	v_fmac_f32_e32 v23, v16, v16
	v_mul_f32_e32 v25, v21, v21
	v_fmac_f32_e32 v24, v18, v18
	v_add_f32_e32 v22, v22, v23
	v_cndmask_b32_e32 v0, v13, v0, vcc
	v_fmac_f32_e32 v25, v20, v20
	v_add_f32_e32 v22, v24, v22
	v_lshlrev_b32_e32 v0, 2, v0
	v_add_f32_e32 v26, v25, v22
	ds_bpermute_b32 v0, v0, v26
	v_cmp_lt_i32_e32 vcc, v93, v92
	global_store_dwordx4 v[90:91], v[14:17], off
	global_store_dwordx4 v[90:91], v[18:21], off offset:16
	v_cndmask_b32_e32 v92, v13, v93, vcc
	v_cvt_pk_bf16_f32 v22, v14, v15
	s_waitcnt lgkmcnt(0)
	v_add_f32_e32 v0, v26, v0
	v_lshlrev_b32_e32 v14, 2, v92
	ds_bpermute_b32 v14, v14, v0
	v_cvt_pk_bf16_f32 v23, v16, v17
	v_lshlrev_b64 v[16:17], 11, v[86:87]
	v_lshl_add_u64 v[16:17], s[70:71], 0, v[16:17]
	v_lshl_add_u64 v[16:17], v[88:89], 1, v[16:17]
	v_cvt_pk_bf16_f32 v24, v18, v19
	v_cvt_pk_bf16_f32 v25, v20, v21
	global_store_dwordx4 v[16:17], v[22:25], off
	s_and_b64 exec, exec, s[8:9]
	s_cbranch_execz .LBB0_2542
	s_lshl_b32 s10, s10, 2
	v_lshl_add_u64 v[16:17], v[8:9], 0, s[10:11]
	s_waitcnt lgkmcnt(0)
	v_add_f32_e32 v0, v0, v14
	global_atomic_add_f32 v[16:17], v0, off
	s_branch .LBB0_2542

;     ...
;         for (int s0 = 0; s0 < ksteps; s0 += 4) {
;             bf16x8 a0[4], a1[4], b0[4], b1[4];
; #pragma unroll
;             for (int j = 0; j < 4; ++j) if (s0 + j < ksteps) { const int s = s0 + j;
;                 a0[j] = *(const bf16x8*)(ap + 32 * s); a1[j] = *(const bf16x8*)(ap + (size_t)16 * lda + 32 * s);
;                 b0[j] = *(const bf16x8*)(bp + 32 * s); b1[j] = *(const bf16x8*)(bp + (size_t)16 * ldb + 32 * s); }
; #pragma unroll
;             for (int j = 0; j < 4; ++j) if (s0 + j < ksteps) {
;                 acc[0][0] = __builtin_amdgcn_mfma_f32_16x16x32_bf16(b0[j], a0[j], acc[0][0], 0, 0, 0); acc[0][1] = __builtin_amdgcn_mfma_f32_16x16x32_bf16(b1[j], a0[j], acc[0][1], 0, 0, 0);
;                 acc[1][0] = __builtin_amdgcn_mfma_f32_16x16x32_bf16(b0[j], a1[j], acc[1][0], 0, 0, 0); acc[1][1] = __builtin_amdgcn_mfma_f32_16x16x32_bf16(b1[j], a1[j], acc[1][1], 0, 0, 0); } }
; #pragma unroll
;         for (int i = 0; i < 2; ++i)
; #pragma unroll
;             for (int j = 0; j < 2; ++j) *(f32x4*)(part + (wid * 32 + 16 * i + fr) * 36 + 16 * j + 4 * fq) = acc[i][j];
;         __syncthreads();
.LBB0_2664:
	s_and_b32 s22, s3, 0xffffffe0
	v_or_b32_e32 v16, s22, v10
	v_ashrrev_i32_e32 v17, 31, v16
	v_lshlrev_b64 v[16:17], 11, v[16:17]
	s_and_b32 s10, s17, 0xe0
	v_lshl_add_u64 v[52:53], v[4:5], 0, v[16:17]
	s_bitset1_b32 s10, 14
	v_or_b32_e32 v0, s10, v10
	v_lshlrev_b32_e32 v0, 11, v0
	v_lshl_add_u64 v[54:55], v[2:3], 0, v[0:1]
	v_add_co_u32_e32 v60, vcc, s19, v54
	v_addc_co_u32_e32 v61, vcc, 0, v55, vcc
	v_add_co_u32_e32 v62, vcc, s19, v52
	v_addc_co_u32_e32 v63, vcc, 0, v53, vcc
	global_load_dwordx4 v[18:21], v[52:53], off
	global_load_dwordx4 v[22:25], v[54:55], off
	global_load_dwordx4 v[26:29], v[60:61], off
	global_load_dwordx4 v[30:33], v[54:55], off offset:64
	global_load_dwordx4 v[34:37], v[52:53], off offset:64
	global_load_dwordx4 v[38:41], v[62:63], off
	global_load_dwordx4 v[42:45], v[60:61], off offset:64
	global_load_dwordx4 v[46:49], v[62:63], off offset:64
	global_load_dwordx4 v[56:59], v[52:53], off offset:128
	global_load_dwordx4 v[64:67], v[54:55], off offset:128
	global_load_dwordx4 v[68:71], v[60:61], off offset:128
	global_load_dwordx4 v[72:75], v[54:55], off offset:192
	global_load_dwordx4 v[76:79], v[52:53], off offset:192
	global_load_dwordx4 v[80:83], v[62:63], off offset:128
	global_load_dwordx4 v[84:87], v[60:61], off offset:192
	global_load_dwordx4 v[88:91], v[62:63], off offset:192
	s_waitcnt vmcnt(14)
	v_mfma_f32_16x16x32_bf16 v[92:95], v[18:21], v[22:25], 0
	s_waitcnt vmcnt(13)
	v_mfma_f32_16x16x32_bf16 v[96:99], v[18:21], v[26:29], 0
	s_waitcnt vmcnt(10)
	v_mfma_f32_16x16x32_bf16 v[100:103], v[38:41], v[22:25], 0
	v_mfma_f32_16x16x32_bf16 v[92:95], v[34:37], v[30:33], v[92:95]
	s_waitcnt vmcnt(9)
	v_mfma_f32_16x16x32_bf16 v[96:99], v[34:37], v[42:45], v[96:99]
	v_mfma_f32_16x16x32_bf16 v[104:107], v[38:41], v[26:29], 0
	s_waitcnt vmcnt(8)
	v_mfma_f32_16x16x32_bf16 v[100:103], v[46:49], v[30:33], v[100:103]
	v_mfma_f32_16x16x32_bf16 v[104:107], v[46:49], v[42:45], v[104:107]
	s_waitcnt vmcnt(6)
	v_mfma_f32_16x16x32_bf16 v[92:95], v[56:59], v[64:67], v[92:95]
	s_waitcnt vmcnt(5)
	v_mfma_f32_16x16x32_bf16 v[96:99], v[56:59], v[68:71], v[96:99]
	s_waitcnt vmcnt(2)
	v_mfma_f32_16x16x32_bf16 v[100:103], v[80:83], v[64:67], v[100:103]
	v_mfma_f32_16x16x32_bf16 v[104:107], v[80:83], v[68:71], v[104:107]
	v_mfma_f32_16x16x32_bf16 v[92:95], v[76:79], v[72:75], v[92:95]
	s_waitcnt vmcnt(1)
	v_mfma_f32_16x16x32_bf16 v[96:99], v[76:79], v[84:87], v[96:99]
	s_waitcnt vmcnt(0)
	v_mfma_f32_16x16x32_bf16 v[100:103], v[88:91], v[72:75], v[100:103]
	v_mfma_f32_16x16x32_bf16 v[104:107], v[88:91], v[84:87], v[104:107]
	s_nop 9
	ds_write_b128 v7, v[92:95]
	ds_write_b128 v7, v[96:99] offset:2304
	ds_write_b128 v7, v[100:103] offset:64
	ds_write_b128 v7, v[104:107] offset:2368
	s_waitcnt lgkmcnt(0)
	s_barrier
	s_and_saveexec_b64 s[12:13], s[6:7]
	s_cbranch_execz .LBB0_2663
; __device__ __forceinline__ float bf_lo(unsigned w) { return __uint_as_float(w << 16); }
; __device__ __forceinline__ float bf_hi(unsigned w) { return __uint_as_float(w & 0xffff0000u); }
; __device__ __forceinline__ float sigmoidf_(float x) { return __builtin_amdgcn_rcpf(1.0f + __expf(-x)); }
; __device__ __forceinline__ float rinv_of(float ssq) { return rsqrtf(ssq * (1.0f / 1024.0f) + EPS); }
; __device__ __forceinline__ u32x4 pack8(const f32x4 a, const f32x4 b) { u32x4 w; w.x = cvt_pk_bf16(a[0], a[1]); w.y = cvt_pk_bf16(a[2], a[3]); w.z = cvt_pk_bf16(b[0], b[1]); w.w = cvt_pk_bf16(b[2], b[3]); return w; }
; __device__ __forceinline__ float sq8(const f32x4 a, const f32x4 b) { return (a[0] * a[0] + a[1] * a[1]) + (a[2] * a[2] + a[3] * a[3]) + (b[0] * b[0] + b[1] * b[1]) + (b[2] * b[2] + b[3] * b[3]); }
;     __device__ __forceinline__ float apply8(int r, int c, const f32x4 a0_, const f32x4 a1_) const {
;         const float ri = rinv_of(ssq_in[r]); float* hp = h + (size_t)r * D + c; const u32x4 pw = *(const u32x4*)(pp + (size_t)r * D + c);
;         const f32x4 a0 = a0_ * ri, a1 = a1_ * ri; f32x4 v0 = *(const f32x4*)hp, v1 = *(const f32x4*)(hp + 4);
;         if (mul == 0.f) { if (hb) *(u32x4*)(hb + (size_t)r * D + c) = pack8(v0, v1); return 0.f; }
;         v0[0] += sigmoidf_(a0[0]) * bf_lo(pw.x); v0[1] += sigmoidf_(a0[1]) * bf_hi(pw.x); v0[2] += sigmoidf_(a0[2]) * bf_lo(pw.y); v0[3] += sigmoidf_(a0[3]) * bf_hi(pw.y);
;         v1[0] += sigmoidf_(a1[0]) * bf_lo(pw.z); v1[1] += sigmoidf_(a1[1]) * bf_hi(pw.z); v1[2] += sigmoidf_(a1[2]) * bf_lo(pw.w); v1[3] += sigmoidf_(a1[3]) * bf_hi(pw.w);
;         *(f32x4*)hp = v0; *(f32x4*)(hp + 4) = v1; if (hb) *(u32x4*)(hb + (size_t)r * D + c) = pack8(v0, v1); return sq8(v0, v1); }
;     ...
;         if (tid < 128) { const int row = tid >> 2, oct = tid & 3; f32x4 v0 = (f32x4){0.f, 0.f, 0.f, 0.f}, v1 = v0;
; #pragma unroll
;             for (int w = 0; w < 8; ++w) { v0 += *(const f32x4*)(part + (w * 32 + row) * 36 + 8 * oct); v1 += *(const f32x4*)(part + (w * 32 + row) * 36 + 8 * oct + 4); }
;             float sq = E.apply8(r0 + row, c0 + 8 * oct, v0, v1);
;             if (Epi::HAS_SSQ) { sq += __shfl_xor(sq, 1); sq += __shfl_xor(sq, 2); if (oct == 0) atomicAdd(E.ssq + r0 + row, sq); } }
	v_add_u32_e32 v52, s10, v6
	v_ashrrev_i32_e32 v53, 31, v52
	v_lshl_add_u64 v[16:17], v[52:53], 2, s[14:15]
	global_load_dword v0, v[16:17], off
	v_or_b32_e32 v54, s22, v11
	v_lshlrev_b64 v[16:17], 11, v[52:53]
	v_ashrrev_i32_e32 v55, 31, v54
	v_lshl_add_u64 v[16:17], s[72:73], 0, v[16:17]
	v_lshlrev_b64 v[52:53], 12, v[52:53]
	v_lshl_add_u64 v[16:17], v[54:55], 1, v[16:17]
	v_lshl_add_u64 v[52:53], s[52:53], 0, v[52:53]
	global_load_dwordx4 v[16:19], v[16:17], off
	v_lshl_add_u64 v[92:93], v[54:55], 2, v[52:53]
	ds_read_b128 v[20:23], v12
	ds_read_b128 v[24:27], v12 offset:16
	ds_read_b128 v[28:31], v12 offset:4624
	ds_read_b128 v[32:35], v12 offset:4608
	ds_read_b128 v[36:39], v12 offset:9232
	ds_read_b128 v[40:43], v12 offset:9216
	ds_read_b128 v[44:47], v12 offset:13840
	ds_read_b128 v[48:51], v12 offset:13824
	global_load_dwordx4 v[52:55], v[92:93], off offset:16
	global_load_dwordx4 v[56:59], v[92:93], off
	s_waitcnt lgkmcnt(7)
	v_pk_add_f32 v[20:21], v[20:21], 0 op_sel_hi:[1,0]
	s_waitcnt lgkmcnt(6)
	v_pk_add_f32 v[26:27], v[26:27], 0 op_sel_hi:[1,0]
	v_pk_add_f32 v[24:25], v[24:25], 0 op_sel_hi:[1,0]
	v_pk_add_f32 v[22:23], v[22:23], 0 op_sel_hi:[1,0]
	s_waitcnt lgkmcnt(4)
	v_pk_add_f32 v[20:21], v[20:21], v[32:33]
	ds_read_b128 v[60:63], v12 offset:18448
	ds_read_b128 v[64:67], v12 offset:18432
	ds_read_b128 v[68:71], v12 offset:23056
	ds_read_b128 v[72:75], v12 offset:23040
	ds_read_b128 v[76:79], v12 offset:27664
	ds_read_b128 v[80:83], v12 offset:27648
	ds_read_b128 v[84:87], v12 offset:32272
	ds_read_b128 v[88:91], v12 offset:32256
	v_pk_add_f32 v[26:27], v[26:27], v[30:31]
	v_pk_add_f32 v[24:25], v[24:25], v[28:29]
	v_pk_add_f32 v[22:23], v[22:23], v[34:35]
	s_waitcnt lgkmcnt(10)
	v_pk_add_f32 v[20:21], v[20:21], v[40:41]
	v_pk_add_f32 v[26:27], v[26:27], v[38:39]
	v_pk_add_f32 v[24:25], v[24:25], v[36:37]
	v_pk_add_f32 v[22:23], v[22:23], v[42:43]
	s_waitcnt lgkmcnt(8)
	v_pk_add_f32 v[20:21], v[20:21], v[48:49]
	v_pk_add_f32 v[26:27], v[26:27], v[46:47]
	v_pk_add_f32 v[24:25], v[24:25], v[44:45]
	v_pk_add_f32 v[22:23], v[22:23], v[50:51]
	s_waitcnt lgkmcnt(6)
	v_pk_add_f32 v[20:21], v[20:21], v[64:65]
	v_pk_add_f32 v[26:27], v[26:27], v[62:63]
	v_pk_add_f32 v[24:25], v[24:25], v[60:61]
	v_pk_add_f32 v[22:23], v[22:23], v[66:67]
	s_waitcnt lgkmcnt(4)
	v_pk_add_f32 v[20:21], v[20:21], v[72:73]
	v_pk_add_f32 v[26:27], v[26:27], v[70:71]
	v_pk_add_f32 v[24:25], v[24:25], v[68:69]
	v_pk_add_f32 v[22:23], v[22:23], v[74:75]
	s_waitcnt lgkmcnt(2)
	v_pk_add_f32 v[20:21], v[20:21], v[80:81]
	v_pk_add_f32 v[26:27], v[26:27], v[78:79]
	v_pk_add_f32 v[24:25], v[24:25], v[76:77]
	v_pk_add_f32 v[22:23], v[22:23], v[82:83]
	s_waitcnt lgkmcnt(0)
	v_pk_add_f32 v[20:21], v[20:21], v[88:89]
	v_pk_add_f32 v[26:27], v[26:27], v[86:87]
	v_pk_add_f32 v[24:25], v[24:25], v[84:85]
	v_pk_add_f32 v[22:23], v[22:23], v[90:91]
	s_waitcnt vmcnt(3)
	v_fmamk_f32 v0, v0, 0x3a800000, v13
	v_mul_f32_e32 v15, 0x4b800000, v0
	v_cmp_gt_f32_e32 vcc, s20, v0
	s_waitcnt vmcnt(2)
	v_lshlrev_b32_e32 v28, 16, v16
	v_cndmask_b32_e32 v0, v0, v15, vcc
	v_rsq_f32_e32 v0, v0
	v_and_b32_e32 v29, 0xffff0000, v16
	v_lshlrev_b32_e32 v16, 16, v17
	v_and_b32_e32 v17, 0xffff0000, v17
	v_mul_f32_e32 v15, 0x45800000, v0
	v_cndmask_b32_e32 v0, v0, v15, vcc
	v_pk_mul_f32 v[20:21], v[20:21], v[0:1] op_sel_hi:[1,0]
	v_pk_mul_f32 v[26:27], v[26:27], v[0:1] op_sel_hi:[1,0]
	v_pk_mul_f32 v[24:25], v[24:25], v[0:1] op_sel_hi:[1,0]
	v_pk_mul_f32 v[22:23], v[22:23], v[0:1] op_sel_hi:[1,0]
	v_mul_f32_e32 v0, 0xbfb8aa3b, v20
	v_mul_f32_e32 v15, 0xbfb8aa3b, v21
	v_mul_f32_e32 v20, 0xbfb8aa3b, v22
	v_exp_f32_e32 v0, v0
	v_mul_f32_e32 v21, 0xbfb8aa3b, v23
	v_exp_f32_e32 v15, v15
	v_exp_f32_e32 v20, v20
	v_exp_f32_e32 v21, v21
	v_add_f32_e32 v0, 1.0, v0
	v_mul_f32_e32 v22, 0xbfb8aa3b, v24
	v_add_f32_e32 v15, 1.0, v15
	v_add_f32_e32 v24, 1.0, v20
	v_rcp_f32_e32 v20, v0
	v_mul_f32_e32 v0, 0xbfb8aa3b, v26
	v_mul_f32_e32 v23, 0xbfb8aa3b, v25
	v_add_f32_e32 v25, 1.0, v21
	v_rcp_f32_e32 v21, v15
	v_exp_f32_e32 v0, v0
	v_mul_f32_e32 v15, 0xbfb8aa3b, v27
	v_exp_f32_e32 v22, v22
	v_exp_f32_e32 v23, v23
	v_exp_f32_e32 v15, v15
	v_add_f32_e32 v0, 1.0, v0
	v_add_f32_e32 v30, 1.0, v22
	v_add_f32_e32 v31, 1.0, v23
	v_rcp_f32_e32 v22, v24
	v_rcp_f32_e32 v23, v25
	v_rcp_f32_e32 v26, v0
	v_add_f32_e32 v0, 1.0, v15
	v_rcp_f32_e32 v24, v30
	v_rcp_f32_e32 v25, v31
	v_rcp_f32_e32 v27, v0
	s_waitcnt vmcnt(0)
	v_pk_fma_f32 v[20:21], v[20:21], v[28:29], v[56:57]
	v_pk_fma_f32 v[22:23], v[22:23], v[16:17], v[58:59]
	v_lshlrev_b32_e32 v16, 16, v18
	v_and_b32_e32 v17, 0xffff0000, v18
	v_lshlrev_b32_e32 v18, 16, v19
	v_and_b32_e32 v19, 0xffff0000, v19
	v_pk_fma_f32 v[16:17], v[24:25], v[16:17], v[52:53]
	v_pk_fma_f32 v[18:19], v[26:27], v[18:19], v[54:55]
	v_pk_mul_f32 v[24:25], v[20:21], v[20:21]
	v_pk_mul_f32 v[26:27], v[22:23], v[22:23]
	v_pk_mul_f32 v[28:29], v[16:17], v[16:17]
	v_add_f32_e32 v0, v26, v27
	v_add_f32_e32 v15, v24, v25
	v_pk_mul_f32 v[30:31], v[18:19], v[18:19]
	v_add_f32_e32 v0, v15, v0
	v_add_f32_e32 v15, v28, v29
	v_add_f32_e32 v0, v15, v0
	v_add_f32_e32 v15, v30, v31
	v_and_b32_e32 v24, 64, v14
	v_add_f32_e32 v0, v15, v0
	v_xor_b32_e32 v15, 1, v14
	v_add_u32_e32 v24, 64, v24
	v_cmp_lt_i32_e32 vcc, v15, v24
	global_store_dwordx4 v[92:93], v[20:23], off
	global_store_dwordx4 v[92:93], v[16:19], off offset:16
	v_cndmask_b32_e32 v15, v14, v15, vcc
	v_lshlrev_b32_e32 v15, 2, v15
	ds_bpermute_b32 v15, v15, v0
	s_waitcnt lgkmcnt(0)
	v_add_f32_e32 v0, v0, v15
	v_xor_b32_e32 v15, 2, v14
	v_cmp_lt_i32_e32 vcc, v15, v24
	s_nop 1
	v_cndmask_b32_e32 v15, v14, v15, vcc
	v_lshlrev_b32_e32 v15, 2, v15
	ds_bpermute_b32 v15, v15, v0
	s_and_b64 exec, exec, s[8:9]
	s_cbranch_execz .LBB0_2663
	s_lshl_b32 s10, s10, 2
	v_lshl_add_u64 v[16:17], v[8:9], 0, s[10:11]
	s_waitcnt lgkmcnt(0)
	v_add_f32_e32 v0, v0, v15
	global_atomic_add_f32 v[16:17], v0, off
	s_branch .LBB0_2663
